# hyena ctx prologue loads batched; attention LDS fragment reads hoisted into free registers with counted waits
# speedup vs baseline: 1.0168x; 1.0044x over previous
.LBB0_1211:
	s_bitcmp1_b32 s10, 0
	s_cselect_b32 s11, 0xb800, 0
	s_setprio 1
	v_or_b32_e32 v80, s11, v94
	v_add_u32_e32 v109, v80, v187
	ds_read_b128 v[220:223], v109
	ds_read_b128 v[224:227], v109 offset:64
	ds_read_b128 v[228:231], v109 offset:3328
	ds_read_b128 v[232:235], v109 offset:6656
	ds_read_b128 v[236:239], v109 offset:9984
	ds_read_b128 v[240:243], v109 offset:3392
	ds_read_b128 v[244:247], v109 offset:6720
	ds_read_b128 v[248:251], v109 offset:10048
	s_waitcnt lgkmcnt(7)
	v_mfma_f32_16x16x32_bf16 v[112:115], v[220:223], v[4:7], v[0:3]
	v_mfma_f32_16x16x32_bf16 v[82:85], v[220:223], v[16:19], v[0:3]
	ds_read_b128 v[220:223], v109 offset:128
	s_waitcnt lgkmcnt(7)
	v_mfma_f32_16x16x32_bf16 v[112:115], v[224:227], v[8:11], v[112:115]
	v_mfma_f32_16x16x32_bf16 v[82:85], v[224:227], v[20:23], v[82:85]
	ds_read_b128 v[224:227], v109 offset:3456
	s_waitcnt lgkmcnt(7)
	v_mfma_f32_16x16x32_bf16 v[120:123], v[228:231], v[4:7], v[0:3]
	v_mfma_f32_16x16x32_bf16 v[116:119], v[228:231], v[16:19], v[0:3]
	ds_read_b128 v[228:231], v109 offset:6784
	s_waitcnt lgkmcnt(5)
	v_mfma_f32_16x16x32_bf16 v[120:123], v[240:243], v[8:11], v[120:123]
	v_mfma_f32_16x16x32_bf16 v[116:119], v[240:243], v[20:23], v[116:119]
	ds_read_b128 v[240:243], v109 offset:10112
	v_mfma_f32_16x16x32_bf16 v[128:131], v[232:235], v[4:7], v[0:3]
	v_mfma_f32_16x16x32_bf16 v[124:127], v[232:235], v[16:19], v[0:3]
	s_waitcnt lgkmcnt(5)
	v_mfma_f32_16x16x32_bf16 v[128:131], v[244:247], v[8:11], v[128:131]
	v_mfma_f32_16x16x32_bf16 v[124:127], v[244:247], v[20:23], v[124:127]
	v_mfma_f32_16x16x32_bf16 v[136:139], v[236:239], v[4:7], v[0:3]
	v_mfma_f32_16x16x32_bf16 v[132:135], v[236:239], v[16:19], v[0:3]
	s_waitcnt lgkmcnt(4)
	v_mfma_f32_16x16x32_bf16 v[136:139], v[248:251], v[8:11], v[136:139]
	v_mfma_f32_16x16x32_bf16 v[132:135], v[248:251], v[20:23], v[132:135]
	s_waitcnt lgkmcnt(3)
	v_mfma_f32_16x16x32_bf16 v[148:151], v[220:223], v[24:27], v[82:85]
	s_waitcnt lgkmcnt(2)
	v_mfma_f32_16x16x32_bf16 v[120:123], v[224:227], v[12:15], v[120:123]
	v_mfma_f32_16x16x32_bf16 v[84:87], v[224:227], v[24:27], v[116:119]
	s_waitcnt lgkmcnt(1)
	v_mfma_f32_16x16x32_bf16 v[152:155], v[228:231], v[12:15], v[128:131]
	v_mfma_f32_16x16x32_bf16 v[156:159], v[228:231], v[24:27], v[124:127]
	v_mfma_f32_16x16x32_bf16 v[112:115], v[220:223], v[12:15], v[112:115]
	s_waitcnt lgkmcnt(0)
	v_mfma_f32_16x16x32_bf16 v[160:163], v[240:243], v[12:15], v[136:139]
	v_mfma_f32_16x16x32_bf16 v[164:167], v[240:243], v[24:27], v[132:135]
	s_nop 2
	s_setprio 0
	s_nop 3
	v_mul_f32_e32 v80, 0x3e16c740, v112
	v_mul_f32_e32 v82, 0x3e16c740, v113
	v_max3_f32 v80, v80, s71, v82
	v_mul_f32_e32 v82, 0x3e16c740, v114
	v_mul_f32_e32 v83, 0x3e16c740, v115
	v_max3_f32 v80, v80, v82, v83
	v_mul_f32_e32 v82, 0x3e16c740, v120
	v_mul_f32_e32 v83, 0x3e16c740, v121
	v_max3_f32 v80, v80, v82, v83
	v_mul_f32_e32 v82, 0x3e16c740, v122
	v_mul_f32_e32 v83, 0x3e16c740, v123
	v_max3_f32 v80, v80, v82, v83
	v_mul_f32_e32 v82, 0x3e16c740, v152
	v_mul_f32_e32 v83, 0x3e16c740, v153
	v_max3_f32 v80, v80, v82, v83
	v_mul_f32_e32 v82, 0x3e16c740, v154
	v_mul_f32_e32 v83, 0x3e16c740, v155
	v_max3_f32 v80, v80, v82, v83
	v_mul_f32_e32 v82, 0x3e16c740, v160
	v_mul_f32_e32 v83, 0x3e16c740, v161
	v_max3_f32 v80, v80, v82, v83
	v_mul_f32_e32 v82, 0x3e16c740, v162
	v_mul_f32_e32 v83, 0x3e16c740, v163
	v_max3_f32 v80, v80, v82, v83
	v_mov_b32_e32 v82, v80
	s_nop 1
	v_permlane16_swap_b32_e32 v80, v82
	v_max_f32_e32 v82, v82, v82
	v_max_f32_e32 v80, v80, v80
	v_max_f32_e32 v80, v80, v82
	v_mov_b32_e32 v82, v80
	s_nop 1
	v_permlane32_swap_b32_e32 v80, v82
	v_max3_f32 v144, v81, v80, v82
	v_sub_f32_e32 v80, v81, v144
	v_fma_f32 v81, v112, s70, -v144
	v_exp_f32_e32 v143, v81
	v_fma_f32 v81, v113, s70, -v144
	v_exp_f32_e32 v141, v81
	v_fma_f32 v81, v114, s70, -v144
	v_mul_f32_e32 v112, 0x3e16c740, v148
	v_mul_f32_e32 v114, 0x3e16c740, v149
	v_max3_f32 v112, v112, s71, v114
	v_mul_f32_e32 v114, 0x3e16c740, v150
	v_mul_f32_e32 v116, 0x3e16c740, v151
	v_max3_f32 v112, v112, v114, v116
	v_mul_f32_e32 v114, 0x3e16c740, v84
	v_mul_f32_e32 v116, 0x3e16c740, v85
	v_max3_f32 v112, v112, v114, v116
	v_mul_f32_e32 v114, 0x3e16c740, v86
	v_mul_f32_e32 v116, 0x3e16c740, v87
	v_max3_f32 v112, v112, v114, v116
	v_mul_f32_e32 v114, 0x3e16c740, v156
	v_mul_f32_e32 v116, 0x3e16c740, v157
	v_max3_f32 v112, v112, v114, v116
	v_mul_f32_e32 v114, 0x3e16c740, v158
	v_mul_f32_e32 v116, 0x3e16c740, v159
	v_max3_f32 v112, v112, v114, v116
	v_mul_f32_e32 v114, 0x3e16c740, v164
	v_mul_f32_e32 v116, 0x3e16c740, v165
	v_max3_f32 v112, v112, v114, v116
	v_mul_f32_e32 v114, 0x3e16c740, v166
	v_mul_f32_e32 v116, 0x3e16c740, v167
	v_max3_f32 v112, v112, v114, v116
	v_mov_b32_e32 v114, v112
	s_nop 1
	v_permlane16_swap_b32_e32 v112, v114
	v_max_f32_e32 v114, v114, v114
	v_max_f32_e32 v112, v112, v112
	v_max_f32_e32 v112, v112, v114
	v_mov_b32_e32 v114, v112
	v_exp_f32_e32 v139, v81
	v_fma_f32 v81, v115, s70, -v144
	v_permlane32_swap_b32_e32 v112, v114
	v_exp_f32_e32 v137, v81
	v_fma_f32 v81, v120, s70, -v144
	v_max3_f32 v146, v190, v112, v114
	v_exp_f32_e32 v135, v81
	v_fma_f32 v81, v121, s70, -v144
	v_fma_f32 v84, v84, s70, -v146
	v_exp_f32_e32 v133, v81
	v_fma_f32 v81, v122, s70, -v144
	v_exp_f32_e32 v134, v84
	v_fma_f32 v84, v85, s70, -v146
	v_exp_f32_e32 v131, v81
	v_fma_f32 v81, v123, s70, -v144
	v_exp_f32_e32 v132, v84
	v_fma_f32 v84, v86, s70, -v146
	v_exp_f32_e32 v129, v81
	v_fma_f32 v81, v152, s70, -v144
	v_exp_f32_e32 v130, v84
	v_fma_f32 v84, v87, s70, -v146
	v_exp_f32_e32 v127, v81
	v_fma_f32 v81, v153, s70, -v144
	v_exp_f32_e32 v128, v84
	v_fma_f32 v84, v156, s70, -v146
	v_exp_f32_e32 v125, v81
	v_fma_f32 v81, v154, s70, -v144
	v_exp_f32_e32 v126, v84
	v_fma_f32 v84, v157, s70, -v146
	v_exp_f32_e32 v123, v81
	v_fma_f32 v81, v155, s70, -v144
	v_fma_f32 v112, v148, s70, -v146
	v_exp_f32_e32 v124, v84
	v_fma_f32 v84, v158, s70, -v146
	v_exp_f32_e32 v119, v81
	v_fma_f32 v81, v160, s70, -v144
	v_exp_f32_e32 v142, v112
	v_fma_f32 v112, v149, s70, -v146
	v_exp_f32_e32 v122, v84
	v_fma_f32 v84, v159, s70, -v146
	v_exp_f32_e32 v115, v81
	v_fma_f32 v81, v161, s70, -v144
	v_exp_f32_e32 v140, v112
	v_fma_f32 v112, v150, s70, -v146
	v_exp_f32_e32 v118, v84
	v_fma_f32 v84, v164, s70, -v146
	v_fma_f32 v85, v166, s70, -v146
	v_exp_f32_e32 v113, v81
	v_fma_f32 v81, v162, s70, -v144
	v_exp_f32_e32 v110, v80
	v_fma_f32 v80, v163, s70, -v144
	v_sub_f32_e32 v116, v190, v146
	v_exp_f32_e32 v138, v112
	v_fma_f32 v112, v151, s70, -v146
	v_exp_f32_e32 v114, v84
	v_fma_f32 v84, v165, s70, -v146
	v_exp_f32_e32 v120, v85
	v_fma_f32 v85, v167, s70, -v146
	v_exp_f32_e32 v121, v81
	v_exp_f32_e32 v117, v80
	v_exp_f32_e32 v136, v112
	v_exp_f32_e32 v112, v84
	v_exp_f32_e32 v84, v116
	v_exp_f32_e32 v116, v85
	v_pk_mul_f32 v[70:71], v[70:71], v[110:111] op_sel_hi:[1,0]
	v_pk_mul_f32 v[68:69], v[68:69], v[110:111] op_sel_hi:[1,0]
	v_pk_mul_f32 v[66:67], v[66:67], v[110:111] op_sel_hi:[1,0]
	v_pk_mul_f32 v[64:65], v[64:65], v[110:111] op_sel_hi:[1,0]
	v_pk_mul_f32 v[74:75], v[74:75], v[110:111] op_sel_hi:[1,0]
	v_pk_mul_f32 v[72:73], v[72:73], v[110:111] op_sel_hi:[1,0]
	v_pk_mul_f32 v[82:83], v[78:79], v[110:111] op_sel_hi:[1,0]
	v_pk_mul_f32 v[80:81], v[76:77], v[110:111] op_sel_hi:[1,0]
	v_cvt_pk_bf16_f32 v152, v143, v141
	v_cvt_pk_bf16_f32 v153, v139, v137
	v_cvt_pk_bf16_f32 v154, v135, v133
	v_cvt_pk_bf16_f32 v155, v131, v129
	v_cvt_pk_bf16_f32 v76, v127, v125
	v_cvt_pk_bf16_f32 v77, v123, v119
	v_cvt_pk_bf16_f32 v78, v115, v113
	v_cvt_pk_bf16_f32 v79, v121, v117
	v_pk_mul_f32 v[54:55], v[54:55], v[84:85] op_sel_hi:[1,0]
	v_pk_mul_f32 v[52:53], v[52:53], v[84:85] op_sel_hi:[1,0]
	v_pk_mul_f32 v[50:51], v[50:51], v[84:85] op_sel_hi:[1,0]
	v_pk_mul_f32 v[48:49], v[48:49], v[84:85] op_sel_hi:[1,0]
	v_pk_mul_f32 v[58:59], v[58:59], v[84:85] op_sel_hi:[1,0]
	v_pk_mul_f32 v[56:57], v[56:57], v[84:85] op_sel_hi:[1,0]
	v_pk_mul_f32 v[62:63], v[62:63], v[84:85] op_sel_hi:[1,0]
	v_pk_mul_f32 v[60:61], v[60:61], v[84:85] op_sel_hi:[1,0]
	v_cvt_pk_bf16_f32 v148, v142, v140
	v_cvt_pk_bf16_f32 v149, v138, v136
	v_cvt_pk_bf16_f32 v150, v134, v132
	v_cvt_pk_bf16_f32 v151, v130, v128
	v_cvt_pk_bf16_f32 v156, v126, v124
	v_cvt_pk_bf16_f32 v157, v122, v118
	v_cvt_pk_bf16_f32 v158, v114, v112
	v_cvt_pk_bf16_f32 v159, v120, v116
	s_setprio 1
	v_add3_u32 v85, s11, v188, v189
	ds_read_b64_tr_b16 v[222:223], v85 offset:29184
	ds_read_b64_tr_b16 v[220:221], v85 offset:26624
	ds_read_b64_tr_b16 v[224:225], v85 offset:26656
	ds_read_b64_tr_b16 v[226:227], v85 offset:29216
	ds_read_b64_tr_b16 v[228:229], v85 offset:31744
	ds_read_b64_tr_b16 v[230:231], v85 offset:34304
	ds_read_b64_tr_b16 v[232:233], v85 offset:31776
	ds_read_b64_tr_b16 v[234:235], v85 offset:34336
	ds_read_b64_tr_b16 v[236:237], v85 offset:26688
	ds_read_b64_tr_b16 v[238:239], v85 offset:29248
	ds_read_b64_tr_b16 v[240:241], v85 offset:31808
	ds_read_b64_tr_b16 v[242:243], v85 offset:34368
	ds_read_b64_tr_b16 v[244:245], v85 offset:26720
	ds_read_b64_tr_b16 v[246:247], v85 offset:29280
	ds_read_b64_tr_b16 v[248:249], v85 offset:31840
	ds_read_b64_tr_b16 v[250:251], v85 offset:34400
	s_waitcnt lgkmcnt(14)
	v_mfma_f32_16x16x32_bf16 v[68:71], v[220:223], v[152:155], v[68:71]
	v_mfma_f32_16x16x32_bf16 v[52:55], v[220:223], v[148:151], v[52:55]
	s_waitcnt lgkmcnt(10)
	v_mfma_f32_16x16x32_bf16 v[68:71], v[228:231], v[76:79], v[68:71]
	v_mfma_f32_16x16x32_bf16 v[52:55], v[228:231], v[156:159], v[52:55]
	v_mfma_f32_16x16x32_bf16 v[64:67], v[224:227], v[152:155], v[64:67]
	v_mfma_f32_16x16x32_bf16 v[48:51], v[224:227], v[148:151], v[48:51]
	s_waitcnt lgkmcnt(8)
	v_mfma_f32_16x16x32_bf16 v[64:67], v[232:235], v[76:79], v[64:67]
	v_mfma_f32_16x16x32_bf16 v[48:51], v[232:235], v[156:159], v[48:51]
	s_waitcnt lgkmcnt(6)
	v_mfma_f32_16x16x32_bf16 v[72:75], v[236:239], v[152:155], v[72:75]
	v_mfma_f32_16x16x32_bf16 v[56:59], v[236:239], v[148:151], v[56:59]
	s_waitcnt lgkmcnt(4)
	v_mfma_f32_16x16x32_bf16 v[72:75], v[240:243], v[76:79], v[72:75]
	v_mfma_f32_16x16x32_bf16 v[56:59], v[240:243], v[156:159], v[56:59]
	s_waitcnt lgkmcnt(2)
	v_mfma_f32_16x16x32_bf16 v[60:63], v[244:247], v[148:151], v[60:63]
	v_mfma_f32_16x16x32_bf16 v[80:83], v[244:247], v[152:155], v[80:83]
	s_waitcnt lgkmcnt(0)
	v_mfma_f32_16x16x32_bf16 v[76:79], v[248:251], v[76:79], v[80:83]
	v_mfma_f32_16x16x32_bf16 v[60:63], v[248:251], v[156:159], v[60:63]
	s_nop 3
	s_setprio 0
	s_setprio 1
	ds_read_b128 v[220:223], v109 offset:13312
	ds_read_b128 v[224:227], v109 offset:13376
	ds_read_b128 v[228:231], v109 offset:16640
	ds_read_b128 v[232:235], v109 offset:19968
	ds_read_b128 v[236:239], v109 offset:23296
	ds_read_b128 v[240:243], v109 offset:16704
	ds_read_b128 v[244:247], v109 offset:20032
	ds_read_b128 v[248:251], v109 offset:23360
	s_waitcnt lgkmcnt(7)
	v_mfma_f32_16x16x32_bf16 v[148:151], v[220:223], v[4:7], v[0:3]
	v_mfma_f32_16x16x32_bf16 v[80:83], v[220:223], v[16:19], v[0:3]
	ds_read_b128 v[220:223], v109 offset:13440
	s_waitcnt lgkmcnt(7)
	v_mfma_f32_16x16x32_bf16 v[148:151], v[224:227], v[8:11], v[148:151]
	v_mfma_f32_16x16x32_bf16 v[80:83], v[224:227], v[20:23], v[80:83]
	ds_read_b128 v[224:227], v109 offset:16768
	s_waitcnt lgkmcnt(7)
	v_mfma_f32_16x16x32_bf16 v[156:159], v[228:231], v[4:7], v[0:3]
	v_mfma_f32_16x16x32_bf16 v[152:155], v[228:231], v[16:19], v[0:3]
	ds_read_b128 v[228:231], v109 offset:20096
	s_waitcnt lgkmcnt(5)
	v_mfma_f32_16x16x32_bf16 v[156:159], v[240:243], v[8:11], v[156:159]
	v_mfma_f32_16x16x32_bf16 v[152:155], v[240:243], v[20:23], v[152:155]
	ds_read_b128 v[240:243], v109 offset:23424
	v_mfma_f32_16x16x32_bf16 v[164:167], v[232:235], v[4:7], v[0:3]
	v_mfma_f32_16x16x32_bf16 v[160:163], v[232:235], v[16:19], v[0:3]
	s_waitcnt lgkmcnt(5)
	v_mfma_f32_16x16x32_bf16 v[164:167], v[244:247], v[8:11], v[164:167]
	v_mfma_f32_16x16x32_bf16 v[160:163], v[244:247], v[20:23], v[160:163]
	v_mfma_f32_16x16x32_bf16 v[190:193], v[236:239], v[4:7], v[0:3]
	v_mfma_f32_16x16x32_bf16 v[168:171], v[236:239], v[16:19], v[0:3]
	s_waitcnt lgkmcnt(4)
	v_mfma_f32_16x16x32_bf16 v[190:193], v[248:251], v[8:11], v[190:193]
	v_mfma_f32_16x16x32_bf16 v[168:171], v[248:251], v[20:23], v[168:171]
	s_waitcnt lgkmcnt(3)
	v_mfma_f32_16x16x32_bf16 v[148:151], v[220:223], v[12:15], v[148:151]
	v_mfma_f32_16x16x32_bf16 v[194:197], v[220:223], v[24:27], v[80:83]
	s_waitcnt lgkmcnt(2)
	v_mfma_f32_16x16x32_bf16 v[198:201], v[224:227], v[12:15], v[156:159]
	v_mfma_f32_16x16x32_bf16 v[202:205], v[224:227], v[24:27], v[152:155]
	s_waitcnt lgkmcnt(1)
	v_mfma_f32_16x16x32_bf16 v[206:209], v[228:231], v[12:15], v[164:167]
	v_mfma_f32_16x16x32_bf16 v[210:213], v[228:231], v[24:27], v[160:163]
	s_waitcnt lgkmcnt(0)
	v_mfma_f32_16x16x32_bf16 v[190:193], v[240:243], v[12:15], v[190:193]
	v_mfma_f32_16x16x32_bf16 v[214:217], v[240:243], v[24:27], v[168:171]
	s_nop 1
	s_setprio 0
	v_mul_f32_e32 v80, 0x3e16c740, v148
	v_mul_f32_e32 v81, 0x3e16c740, v149
	v_max3_f32 v80, v80, s71, v81
	v_mul_f32_e32 v81, 0x3e16c740, v150
	v_mul_f32_e32 v82, 0x3e16c740, v151
	v_max3_f32 v80, v80, v81, v82
	v_mul_f32_e32 v81, 0x3e16c740, v198
	v_mul_f32_e32 v82, 0x3e16c740, v199
	v_max3_f32 v80, v80, v81, v82
	v_mul_f32_e32 v81, 0x3e16c740, v200
	v_mul_f32_e32 v82, 0x3e16c740, v201
	v_max3_f32 v80, v80, v81, v82
	v_mul_f32_e32 v81, 0x3e16c740, v206
	v_mul_f32_e32 v82, 0x3e16c740, v207
	v_max3_f32 v80, v80, v81, v82
	v_mul_f32_e32 v81, 0x3e16c740, v208
	v_mul_f32_e32 v82, 0x3e16c740, v209
	v_max3_f32 v80, v80, v81, v82
	v_mul_f32_e32 v81, 0x3e16c740, v190
	v_mul_f32_e32 v82, 0x3e16c740, v191
	v_max3_f32 v80, v80, v81, v82
	v_mul_f32_e32 v81, 0x3e16c740, v192
	v_mul_f32_e32 v82, 0x3e16c740, v193
	v_max3_f32 v80, v80, v81, v82
	v_mov_b32_e32 v81, v80
	s_nop 1
	v_permlane16_swap_b32_e32 v80, v81
	v_max_f32_e32 v81, v81, v81
	v_max_f32_e32 v80, v80, v80
	v_max_f32_e32 v80, v80, v81
	v_mov_b32_e32 v81, v80
	s_nop 1
	v_permlane32_swap_b32_e32 v80, v81
	v_max3_f32 v81, v144, v80, v81
	v_fma_f32 v82, v148, s70, -v81
	v_exp_f32_e32 v171, v82
	v_fma_f32 v82, v149, s70, -v81
	v_exp_f32_e32 v169, v82
	v_fma_f32 v82, v150, s70, -v81
	v_exp_f32_e32 v167, v82
	v_fma_f32 v82, v151, s70, -v81
	v_exp_f32_e32 v165, v82
	v_fma_f32 v82, v198, s70, -v81
	v_exp_f32_e32 v163, v82
	v_fma_f32 v82, v199, s70, -v81
	v_exp_f32_e32 v161, v82
	v_fma_f32 v82, v200, s70, -v81
	v_exp_f32_e32 v159, v82
	v_fma_f32 v82, v201, s70, -v81
	v_exp_f32_e32 v157, v82
	v_fma_f32 v82, v206, s70, -v81
	v_exp_f32_e32 v155, v82
	v_fma_f32 v82, v207, s70, -v81
	v_exp_f32_e32 v153, v82
	v_fma_f32 v82, v208, s70, -v81
	v_exp_f32_e32 v151, v82
	v_fma_f32 v82, v209, s70, -v81
	v_exp_f32_e32 v147, v82
	v_fma_f32 v82, v190, s70, -v81
	v_exp_f32_e32 v87, v82
	v_fma_f32 v82, v191, s70, -v81
	v_exp_f32_e32 v83, v82
	v_fma_f32 v82, v192, s70, -v81
	v_exp_f32_e32 v149, v82
	v_fma_f32 v82, v193, s70, -v81
	v_exp_f32_e32 v145, v82
	v_mul_f32_e32 v82, 0x3e16c740, v194
	v_mul_f32_e32 v86, 0x3e16c740, v195
	v_max3_f32 v82, v82, s71, v86
	v_mul_f32_e32 v86, 0x3e16c740, v196
	v_mul_f32_e32 v109, 0x3e16c740, v197
	v_max3_f32 v82, v82, v86, v109
	v_mul_f32_e32 v86, 0x3e16c740, v202
	v_mul_f32_e32 v109, 0x3e16c740, v203
	v_max3_f32 v82, v82, v86, v109
	v_mul_f32_e32 v86, 0x3e16c740, v204
	v_mul_f32_e32 v109, 0x3e16c740, v205
	v_max3_f32 v82, v82, v86, v109
	v_mul_f32_e32 v86, 0x3e16c740, v210
	v_mul_f32_e32 v109, 0x3e16c740, v211
	v_max3_f32 v82, v82, v86, v109
	v_mul_f32_e32 v86, 0x3e16c740, v212
	v_mul_f32_e32 v109, 0x3e16c740, v213
	v_max3_f32 v82, v82, v86, v109
	v_mul_f32_e32 v86, 0x3e16c740, v214
	v_mul_f32_e32 v109, 0x3e16c740, v215
	v_max3_f32 v82, v82, v86, v109
	v_mul_f32_e32 v86, 0x3e16c740, v216
	v_mul_f32_e32 v109, 0x3e16c740, v217
	v_max3_f32 v82, v82, v86, v109
	v_mov_b32_e32 v86, v82
	s_nop 1
	v_permlane16_swap_b32_e32 v82, v86
	v_max_f32_e32 v86, v86, v86
	v_max_f32_e32 v82, v82, v82
	v_max_f32_e32 v82, v82, v86
	v_mov_b32_e32 v86, v82
	s_nop 1
	v_permlane32_swap_b32_e32 v82, v86
	v_max3_f32 v190, v146, v82, v86
	v_fma_f32 v82, v194, s70, -v190
	v_exp_f32_e32 v170, v82
	v_fma_f32 v82, v195, s70, -v190
	v_exp_f32_e32 v168, v82
	v_fma_f32 v82, v196, s70, -v190
	v_exp_f32_e32 v166, v82
	v_fma_f32 v82, v197, s70, -v190
	v_exp_f32_e32 v164, v82
	v_fma_f32 v82, v202, s70, -v190
	v_exp_f32_e32 v162, v82
	v_fma_f32 v82, v203, s70, -v190
	v_exp_f32_e32 v160, v82
	v_fma_f32 v82, v204, s70, -v190
	v_exp_f32_e32 v158, v82
	v_fma_f32 v82, v205, s70, -v190
	v_exp_f32_e32 v156, v82
	v_fma_f32 v82, v210, s70, -v190
	v_exp_f32_e32 v154, v82
	v_fma_f32 v82, v211, s70, -v190
	v_exp_f32_e32 v152, v82
	v_fma_f32 v82, v212, s70, -v190
	v_exp_f32_e32 v150, v82
	v_fma_f32 v82, v213, s70, -v190
	v_sub_f32_e32 v80, v144, v81
	v_sub_f32_e32 v109, v146, v190
	v_exp_f32_e32 v146, v82
	v_fma_f32 v82, v214, s70, -v190
	v_exp_f32_e32 v80, v80
	v_exp_f32_e32 v86, v82
	v_fma_f32 v82, v215, s70, -v190
	v_fma_f32 v144, v216, s70, -v190
	v_exp_f32_e32 v172, v109
	v_fma_f32 v109, v217, s70, -v190
	v_exp_f32_e32 v82, v82
	v_exp_f32_e32 v148, v144
	v_exp_f32_e32 v144, v109
	v_pk_mul_f32 v[70:71], v[70:71], v[80:81] op_sel_hi:[1,0]
	v_pk_mul_f32 v[68:69], v[68:69], v[80:81] op_sel_hi:[1,0]
	v_pk_mul_f32 v[66:67], v[66:67], v[80:81] op_sel_hi:[1,0]
	v_pk_mul_f32 v[64:65], v[64:65], v[80:81] op_sel_hi:[1,0]
	v_pk_mul_f32 v[74:75], v[74:75], v[80:81] op_sel_hi:[1,0]
	v_pk_mul_f32 v[72:73], v[72:73], v[80:81] op_sel_hi:[1,0]
	v_pk_mul_f32 v[200:201], v[78:79], v[80:81] op_sel_hi:[1,0]
	v_pk_mul_f32 v[198:199], v[76:77], v[80:81] op_sel_hi:[1,0]
	v_cvt_pk_bf16_f32 v76, v155, v153
	v_cvt_pk_bf16_f32 v77, v151, v147
	v_cvt_pk_bf16_f32 v78, v87, v83
	v_cvt_pk_bf16_f32 v79, v149, v145
	v_pk_mul_f32 v[54:55], v[54:55], v[172:173] op_sel_hi:[1,0]
	v_pk_mul_f32 v[52:53], v[52:53], v[172:173] op_sel_hi:[1,0]
	v_pk_mul_f32 v[50:51], v[50:51], v[172:173] op_sel_hi:[1,0]
	v_pk_mul_f32 v[48:49], v[48:49], v[172:173] op_sel_hi:[1,0]
	v_pk_mul_f32 v[58:59], v[58:59], v[172:173] op_sel_hi:[1,0]
	v_pk_mul_f32 v[56:57], v[56:57], v[172:173] op_sel_hi:[1,0]
	v_pk_mul_f32 v[62:63], v[62:63], v[172:173] op_sel_hi:[1,0]
	v_pk_mul_f32 v[60:61], v[60:61], v[172:173] op_sel_hi:[1,0]
	v_cvt_pk_bf16_f32 v206, v171, v169
	v_cvt_pk_bf16_f32 v207, v167, v165
	v_cvt_pk_bf16_f32 v208, v163, v161
	v_cvt_pk_bf16_f32 v209, v159, v157
	v_cvt_pk_bf16_f32 v192, v170, v168
	v_cvt_pk_bf16_f32 v193, v166, v164
	v_cvt_pk_bf16_f32 v194, v162, v160
	v_cvt_pk_bf16_f32 v195, v158, v156
	v_cvt_pk_bf16_f32 v202, v154, v152
	v_cvt_pk_bf16_f32 v203, v150, v146
	v_cvt_pk_bf16_f32 v204, v86, v82
	v_cvt_pk_bf16_f32 v205, v148, v144
	s_setprio 1
	ds_read_b64_tr_b16 v[222:223], v85 offset:39424
	ds_read_b64_tr_b16 v[220:221], v85 offset:36864
	ds_read_b64_tr_b16 v[224:225], v85 offset:36896
	ds_read_b64_tr_b16 v[226:227], v85 offset:39456
	ds_read_b64_tr_b16 v[228:229], v85 offset:41984
	ds_read_b64_tr_b16 v[230:231], v85 offset:44544
	ds_read_b64_tr_b16 v[232:233], v85 offset:42016
	ds_read_b64_tr_b16 v[234:235], v85 offset:44576
	ds_read_b64_tr_b16 v[236:237], v85 offset:36928
	ds_read_b64_tr_b16 v[238:239], v85 offset:39488
	ds_read_b64_tr_b16 v[240:241], v85 offset:42048
	ds_read_b64_tr_b16 v[242:243], v85 offset:44608
	ds_read_b64_tr_b16 v[244:245], v85 offset:36960
	ds_read_b64_tr_b16 v[246:247], v85 offset:39520
	ds_read_b64_tr_b16 v[248:249], v85 offset:42080
	ds_read_b64_tr_b16 v[250:251], v85 offset:44640
	s_waitcnt lgkmcnt(14)
	v_mfma_f32_16x16x32_bf16 v[68:71], v[220:223], v[206:209], v[68:71]
	v_mfma_f32_16x16x32_bf16 v[52:55], v[220:223], v[192:195], v[52:55]
	s_waitcnt lgkmcnt(10)
	v_mfma_f32_16x16x32_bf16 v[68:71], v[228:231], v[76:79], v[68:71]
	v_mfma_f32_16x16x32_bf16 v[52:55], v[228:231], v[202:205], v[52:55]
	v_mfma_f32_16x16x32_bf16 v[64:67], v[224:227], v[206:209], v[64:67]
	v_mfma_f32_16x16x32_bf16 v[48:51], v[224:227], v[192:195], v[48:51]
	s_waitcnt lgkmcnt(8)
	v_mfma_f32_16x16x32_bf16 v[64:67], v[232:235], v[76:79], v[64:67]
	v_mfma_f32_16x16x32_bf16 v[48:51], v[232:235], v[202:205], v[48:51]
	s_waitcnt lgkmcnt(6)
	v_mfma_f32_16x16x32_bf16 v[72:75], v[236:239], v[206:209], v[72:75]
	v_mfma_f32_16x16x32_bf16 v[56:59], v[236:239], v[192:195], v[56:59]
	s_waitcnt lgkmcnt(4)
	v_mfma_f32_16x16x32_bf16 v[72:75], v[240:243], v[76:79], v[72:75]
	v_mfma_f32_16x16x32_bf16 v[56:59], v[240:243], v[202:205], v[56:59]
	s_waitcnt lgkmcnt(2)
	v_mfma_f32_16x16x32_bf16 v[60:63], v[244:247], v[192:195], v[60:63]
	v_mfma_f32_16x16x32_bf16 v[196:199], v[244:247], v[206:209], v[198:201]
	s_waitcnt lgkmcnt(0)
	v_mfma_f32_16x16x32_bf16 v[76:79], v[248:251], v[76:79], v[196:199]
	v_mfma_f32_16x16x32_bf16 v[60:63], v[248:251], v[202:205], v[60:63]
	s_nop 3
	s_setprio 0
	s_add_i32 s22, s10, 1
	s_cmp_ge_u32 s22, s19
	s_cbranch_scc1 .LBB0_1213
	s_bitcmp1_b32 s22, 0
	s_cselect_b32 s11, 0xb800, 0
	v_add3_u32 v85, s11, v95, v96
	s_waitcnt vmcnt(0)
	ds_write_b128 v85, v[28:31]
	v_add3_u32 v85, s11, v99, v96
	ds_write_b128 v85, v[36:39]
	v_add3_u32 v85, s11, v185, v96
	ds_write_b128 v85, v[32:35] offset:26624
	v_add3_u32 v85, s11, v186, v96
	ds_write_b128 v85, v[40:43] offset:26624
	v_add3_u32 v85, s11, v111, v98
	ds_write_b128 v85, v[44:47] offset:128

.LBB0_1263:
	s_and_b64 s[16:17], s[6:7], exec
	s_mov_b32 s16, 0xd7f2000
	s_cselect_b32 s16, s16, 0xddf2000
	s_add_u32 s16, s8, s16
	s_addc_u32 s17, s9, 0
	v_lshl_add_u64 v[136:137], v[20:21], 1, s[16:17]
	s_mov_b64 s[16:17], 0x3000
	v_lshl_add_u64 v[136:137], v[136:137], 0, s[16:17]
	global_load_dwordx2 v[140:141], v[136:137], off offset:-4096
	global_load_dwordx2 v[142:143], v[136:137], off
	v_lshl_add_u64 v[138:139], v[136:137], 0, s[52:53]
	global_load_dwordx2 v[144:145], v[138:139], off offset:-4096
	global_load_dwordx2 v[146:147], v[138:139], off
	s_andn2_b64 vcc, exec, s[10:11]
	v_mov_b32_e32 v7, v0
	v_mov_b32_e32 v6, v0
	v_mov_b32_e32 v5, v0
	v_mov_b32_e32 v4, v0
	v_mov_b32_e32 v11, v0
	v_mov_b32_e32 v10, v0
	v_mov_b32_e32 v9, v0
	v_mov_b32_e32 v8, v0
	v_mov_b32_e32 v15, v0
	v_mov_b32_e32 v14, v0
	v_mov_b32_e32 v13, v0
	v_mov_b32_e32 v12, v0
	v_mov_b32_e32 v19, v0
	v_mov_b32_e32 v18, v0
	v_mov_b32_e32 v17, v0
	v_mov_b32_e32 v16, v0
	s_cbranch_vccnz .LBB0_1266
	v_or_b32_e32 v4, s12, v36
	s_and_b64 s[12:13], s[6:7], exec
	s_movk_i32 s12, 0x5380
	s_cselect_b32 s12, s12, 0xa380
	s_movk_i32 s13, 0x1060
	v_mad_u32_u24 v30, v4, s13, v38
	v_add_u32_e32 v31, s12, v39
	s_mov_b32 s12, s18
	v_mov_b32_e32 v16, v0
	v_mov_b32_e32 v17, v0
	v_mov_b32_e32 v18, v0
	v_mov_b32_e32 v19, v0
	v_mov_b32_e32 v12, v0
	v_mov_b32_e32 v13, v0
	v_mov_b32_e32 v14, v0
	v_mov_b32_e32 v15, v0
	v_mov_b32_e32 v8, v0
	v_mov_b32_e32 v9, v0
	v_mov_b32_e32 v10, v0
	v_mov_b32_e32 v11, v0
	v_mov_b32_e32 v4, v0
	v_mov_b32_e32 v5, v0
	v_mov_b32_e32 v6, v0
	v_mov_b32_e32 v7, v0

.Lhy_lat0_done:
.LBB0_1266:
	s_xor_b64 s[12:13], s[6:7], -1
	s_and_b64 s[16:17], s[6:7], exec
	s_cselect_b32 s16, s82, 0xddf2000
	s_add_u32 s16, s8, s16
	s_addc_u32 s17, s9, 0
	v_cndmask_b32_e64 v30, v35, v34, s[6:7]
	s_and_b64 s[6:7], s[6:7], exec
	s_mov_b32 s6, 0x9380
	s_cselect_b32 s6, 0x4380, s6
	v_lshl_add_u64 v[32:33], v[20:21], 1, s[16:17]
	v_lshl_add_u32 v31, v20, 1, s6
	s_movk_i32 s6, 0x2000
	v_add_co_u32_e32 v42, vcc, s6, v32
	ds_read_b64 v[40:41], v31
	s_nop 0
	v_addc_co_u32_e32 v43, vcc, 0, v33, vcc
	v_mov_b32_e32 v49, v18
	s_waitcnt lgkmcnt(0)
	v_lshlrev_b32_e32 v47, 16, v41
	v_lshlrev_b32_e32 v46, 16, v40
	v_and_b32_e32 v41, 0xffff0000, v41
	v_and_b32_e32 v40, 0xffff0000, v40
	v_mov_b32_e32 v18, v17
	v_mov_b32_e32 v48, v16
	v_pk_fma_f32 v[16:17], v[30:31], v[40:41], v[18:19] op_sel_hi:[0,1,1]
	v_pk_fma_f32 v[46:47], v[30:31], v[46:47], v[48:49] op_sel_hi:[0,1,1]
	s_mov_b64 s[6:7], -1
	s_and_b64 vcc, exec, s[12:13]
	s_waitcnt vmcnt(0)
	v_lshlrev_b32_e32 v45, 16, v141
	v_lshlrev_b32_e32 v44, 16, v140
	v_and_b32_e32 v43, 0xffff0000, v141
	v_and_b32_e32 v42, 0xffff0000, v140
	v_pk_mul_f32 v[16:17], v[16:17], v[42:43]
	v_pk_mul_f32 v[44:45], v[46:47], v[44:45]
	v_and_b32_sdwa v31, v17, v177 dst_sel:DWORD dst_unused:UNUSED_PAD src0_sel:WORD_1 src1_sel:DWORD
	v_and_b32_sdwa v40, v16, v177 dst_sel:DWORD dst_unused:UNUSED_PAD src0_sel:WORD_1 src1_sel:DWORD
	v_and_b32_sdwa v18, v45, v177 dst_sel:DWORD dst_unused:UNUSED_PAD src0_sel:WORD_1 src1_sel:DWORD
	v_and_b32_sdwa v19, v44, v177 dst_sel:DWORD dst_unused:UNUSED_PAD src0_sel:WORD_1 src1_sel:DWORD
	v_add3_u32 v17, v17, v31, s60
	v_add3_u32 v16, v16, v40, s60
	v_add3_u32 v19, v44, v19, s60
	v_add3_u32 v18, v45, v18, s60
	v_and_b32_e32 v17, 0xffff0000, v17
	v_and_b32_e32 v16, 0xffff0000, v16
	v_or_b32_sdwa v17, v17, v18 dst_sel:DWORD dst_unused:UNUSED_PAD src0_sel:DWORD src1_sel:WORD_1
	v_or_b32_sdwa v16, v16, v19 dst_sel:DWORD dst_unused:UNUSED_PAD src0_sel:DWORD src1_sel:WORD_1
	s_cbranch_vccz .LBB0_1268
	flat_store_dwordx2 v[22:23], v[16:17]
	s_mov_b64 s[6:7], 0

.LBB0_1270:
	v_lshl_add_u64 v[16:17], v[32:33], 0, s[52:53]
	v_add_co_u32_e32 v32, vcc, 0x1000, v16
	v_lshl_add_u32 v18, v20, 1, s6
	s_nop 0
	v_addc_co_u32_e32 v33, vcc, 0, v17, vcc
	ds_read_b64 v[18:19], v18 offset:512
	v_mov_b32_e32 v31, v30
	v_mov_b32_e32 v45, v14
	v_mov_b32_e32 v14, v13
	v_mov_b32_e32 v44, v12
	s_waitcnt lgkmcnt(0)
	v_lshlrev_b32_e32 v43, 16, v19
	v_lshlrev_b32_e32 v42, 16, v18
	v_and_b32_e32 v19, 0xffff0000, v19
	v_and_b32_e32 v18, 0xffff0000, v18
	v_pk_fma_f32 v[12:13], v[30:31], v[18:19], v[14:15]
	v_pk_fma_f32 v[42:43], v[30:31], v[42:43], v[44:45]
	s_mov_b64 s[16:17], -1
	s_andn2_b64 vcc, exec, s[12:13]
	v_lshlrev_b32_e32 v41, 16, v143
	v_lshlrev_b32_e32 v40, 16, v142
	v_and_b32_e32 v33, 0xffff0000, v143
	v_and_b32_e32 v32, 0xffff0000, v142
	v_pk_mul_f32 v[12:13], v[12:13], v[32:33]
	v_pk_mul_f32 v[40:41], v[42:43], v[40:41]
	v_and_b32_sdwa v18, v13, v177 dst_sel:DWORD dst_unused:UNUSED_PAD src0_sel:WORD_1 src1_sel:DWORD
	v_and_b32_sdwa v14, v41, v177 dst_sel:DWORD dst_unused:UNUSED_PAD src0_sel:WORD_1 src1_sel:DWORD
	v_and_b32_sdwa v19, v12, v177 dst_sel:DWORD dst_unused:UNUSED_PAD src0_sel:WORD_1 src1_sel:DWORD
	v_add3_u32 v13, v13, v18, s60
	v_and_b32_sdwa v15, v40, v177 dst_sel:DWORD dst_unused:UNUSED_PAD src0_sel:WORD_1 src1_sel:DWORD
	v_add3_u32 v14, v41, v14, s60
	v_add3_u32 v12, v12, v19, s60
	v_and_b32_e32 v13, 0xffff0000, v13
	v_add3_u32 v15, v40, v15, s60
	v_and_b32_e32 v12, 0xffff0000, v12
	v_or_b32_sdwa v13, v13, v14 dst_sel:DWORD dst_unused:UNUSED_PAD src0_sel:DWORD src1_sel:WORD_1
	v_cndmask_b32_e64 v14, 0, 1, s[12:13]
	v_or_b32_sdwa v12, v12, v15 dst_sel:DWORD dst_unused:UNUSED_PAD src0_sel:DWORD src1_sel:WORD_1
	v_cmp_ne_u32_e64 s[6:7], 1, v14
	s_cbranch_vccnz .LBB0_1272
	s_mov_b64 s[16:17], 0
	flat_store_dwordx2 v[24:25], v[12:13]

.LBB0_1274:
	v_add_co_u32_e32 v14, vcc, 0x2000, v16
	v_lshl_add_u32 v12, v20, 1, s12
	s_nop 0
	v_addc_co_u32_e32 v15, vcc, 0, v17, vcc
	ds_read_b64 v[12:13], v12 offset:512
	v_mov_b32_e32 v41, v10
	v_mov_b32_e32 v10, v9
	v_mov_b32_e32 v40, v8
	s_mov_b64 s[12:13], -1
	s_waitcnt lgkmcnt(0)
	v_lshlrev_b32_e32 v33, 16, v13
	v_lshlrev_b32_e32 v32, 16, v12
	v_and_b32_e32 v13, 0xffff0000, v13
	v_and_b32_e32 v12, 0xffff0000, v12
	v_pk_fma_f32 v[8:9], v[30:31], v[12:13], v[10:11]
	v_pk_fma_f32 v[32:33], v[30:31], v[32:33], v[40:41]
	s_and_b64 vcc, exec, s[6:7]
	v_lshlrev_b32_e32 v19, 16, v145
	v_lshlrev_b32_e32 v18, 16, v144
	v_and_b32_e32 v15, 0xffff0000, v145
	v_and_b32_e32 v14, 0xffff0000, v144
	v_pk_mul_f32 v[8:9], v[8:9], v[14:15]
	v_pk_mul_f32 v[18:19], v[32:33], v[18:19]
	v_and_b32_sdwa v12, v9, v177 dst_sel:DWORD dst_unused:UNUSED_PAD src0_sel:WORD_1 src1_sel:DWORD
	v_and_b32_sdwa v13, v8, v177 dst_sel:DWORD dst_unused:UNUSED_PAD src0_sel:WORD_1 src1_sel:DWORD
	v_and_b32_sdwa v10, v19, v177 dst_sel:DWORD dst_unused:UNUSED_PAD src0_sel:WORD_1 src1_sel:DWORD
	v_and_b32_sdwa v11, v18, v177 dst_sel:DWORD dst_unused:UNUSED_PAD src0_sel:WORD_1 src1_sel:DWORD
	v_add3_u32 v9, v9, v12, s60
	v_add3_u32 v8, v8, v13, s60
	v_add3_u32 v11, v18, v11, s60
	v_add3_u32 v10, v19, v10, s60
	v_and_b32_e32 v9, 0xffff0000, v9
	v_and_b32_e32 v8, 0xffff0000, v8
	v_or_b32_sdwa v9, v9, v10 dst_sel:DWORD dst_unused:UNUSED_PAD src0_sel:DWORD src1_sel:WORD_1
	v_or_b32_sdwa v8, v8, v11 dst_sel:DWORD dst_unused:UNUSED_PAD src0_sel:DWORD src1_sel:WORD_1
	s_cbranch_vccnz .LBB0_1276
	s_mov_b64 s[12:13], 0
	flat_store_dwordx2 v[26:27], v[8:9]

.LBB0_1278:
	v_add_co_u32_e32 v10, vcc, 0x3000, v16
	v_lshl_add_u32 v8, v20, 1, s12
	s_nop 0
	v_addc_co_u32_e32 v11, vcc, 0, v17, vcc
	ds_read_b64 v[8:9], v8 offset:512
	v_mov_b32_e32 v17, v6
	v_mov_b32_e32 v6, v5
	v_mov_b32_e32 v16, v4
	s_mov_b64 s[12:13], -1
	s_waitcnt lgkmcnt(0)
	v_lshlrev_b32_e32 v15, 16, v9
	v_lshlrev_b32_e32 v14, 16, v8
	v_and_b32_e32 v9, 0xffff0000, v9
	v_and_b32_e32 v8, 0xffff0000, v8
	v_pk_fma_f32 v[4:5], v[30:31], v[8:9], v[6:7]
	v_pk_fma_f32 v[14:15], v[30:31], v[14:15], v[16:17]
	s_and_b64 vcc, exec, s[6:7]
	v_lshlrev_b32_e32 v13, 16, v147
	v_lshlrev_b32_e32 v12, 16, v146
	v_and_b32_e32 v11, 0xffff0000, v147
	v_and_b32_e32 v10, 0xffff0000, v146
	v_pk_mul_f32 v[4:5], v[4:5], v[10:11]
	v_pk_mul_f32 v[12:13], v[14:15], v[12:13]
	v_and_b32_sdwa v8, v5, v177 dst_sel:DWORD dst_unused:UNUSED_PAD src0_sel:WORD_1 src1_sel:DWORD
	v_and_b32_sdwa v9, v4, v177 dst_sel:DWORD dst_unused:UNUSED_PAD src0_sel:WORD_1 src1_sel:DWORD
	v_and_b32_sdwa v6, v13, v177 dst_sel:DWORD dst_unused:UNUSED_PAD src0_sel:WORD_1 src1_sel:DWORD
	v_and_b32_sdwa v7, v12, v177 dst_sel:DWORD dst_unused:UNUSED_PAD src0_sel:WORD_1 src1_sel:DWORD
	v_add3_u32 v5, v5, v8, s60
	v_add3_u32 v4, v4, v9, s60
	v_add3_u32 v7, v12, v7, s60
	v_add3_u32 v6, v13, v6, s60
	v_and_b32_e32 v5, 0xffff0000, v5
	v_and_b32_e32 v4, 0xffff0000, v4
	v_or_b32_sdwa v5, v5, v6 dst_sel:DWORD dst_unused:UNUSED_PAD src0_sel:DWORD src1_sel:WORD_1
	v_or_b32_sdwa v4, v4, v7 dst_sel:DWORD dst_unused:UNUSED_PAD src0_sel:DWORD src1_sel:WORD_1
	s_cbranch_vccnz .LBB0_1280
	s_mov_b64 s[12:13], 0
	flat_store_dwordx2 v[28:29], v[4:5]

.LBB0_1301:
	s_bitcmp1_b32 s33, 0
	s_cselect_b32 s78, 0x9800, 0
	s_cmp_lt_i32 s33, s92
	s_cselect_b64 s[6:7], -1, 0
	s_and_b64 s[76:77], s[72:73], s[6:7]
	s_setprio 1
	v_or_b32_e32 v68, s78, v94
	v_add_u32_e32 v88, v68, v163
	ds_read_b128 v[204:207], v88 offset:2304
	ds_read_b128 v[208:211], v88
	ds_read_b128 v[212:215], v88 offset:4608
	ds_read_b128 v[216:219], v88 offset:6912
	ds_read_b128 v[220:223], v88 offset:64
	ds_read_b128 v[224:227], v88 offset:2368
	ds_read_b128 v[228:231], v88 offset:4672
	ds_read_b128 v[232:235], v88 offset:6976
	s_waitcnt lgkmcnt(7)
	v_mfma_f32_16x16x32_bf16 v[82:85], v[204:207], v[4:7], v[0:3]
	v_mfma_f32_16x16x32_bf16 v[108:111], v[204:207], v[12:15], v[0:3]
	s_waitcnt lgkmcnt(5)
	v_mfma_f32_16x16x32_bf16 v[112:115], v[212:215], v[4:7], v[0:3]
	v_mfma_f32_16x16x32_bf16 v[116:119], v[212:215], v[12:15], v[0:3]
	s_waitcnt lgkmcnt(4)
	v_mfma_f32_16x16x32_bf16 v[120:123], v[216:219], v[4:7], v[0:3]
	v_mfma_f32_16x16x32_bf16 v[124:127], v[216:219], v[12:15], v[0:3]
	v_mfma_f32_16x16x32_bf16 v[74:77], v[208:211], v[4:7], v[0:3]
	v_mfma_f32_16x16x32_bf16 v[68:71], v[208:211], v[12:15], v[0:3]
	s_waitcnt lgkmcnt(3)
	v_mfma_f32_16x16x32_bf16 v[128:131], v[220:223], v[8:11], v[74:77]
	v_mfma_f32_16x16x32_bf16 v[76:79], v[220:223], v[16:19], v[68:71]
	s_waitcnt lgkmcnt(2)
	v_mfma_f32_16x16x32_bf16 v[132:135], v[224:227], v[8:11], v[82:85]
	v_mfma_f32_16x16x32_bf16 v[80:83], v[224:227], v[16:19], v[108:111]
	s_waitcnt lgkmcnt(1)
	v_mfma_f32_16x16x32_bf16 v[108:111], v[228:231], v[8:11], v[112:115]
	v_mfma_f32_16x16x32_bf16 v[84:87], v[228:231], v[16:19], v[116:119]
	s_waitcnt lgkmcnt(0)
	v_mfma_f32_16x16x32_bf16 v[112:115], v[232:235], v[8:11], v[120:123]
	v_mfma_f32_16x16x32_bf16 v[142:145], v[232:235], v[16:19], v[124:127]
	s_nop 1
	s_setprio 0
	v_add_u32_e32 v69, 0x73, v166
	v_cmp_gt_u32_e32 vcc, s83, v69
	v_add_u32_e32 v70, 0x72, v166
	s_and_b64 s[12:13], s[76:77], vcc
	v_cmp_gt_u32_e32 vcc, s83, v70
	v_add_u32_e32 v72, 0x71, v166
	s_and_b64 s[14:15], s[76:77], vcc
	v_cmp_gt_u32_e32 vcc, s83, v72
	v_add_u32_e32 v74, 0x70, v166
	s_and_b64 s[16:17], s[76:77], vcc
	v_cmp_gt_u32_e32 vcc, s83, v74
	v_add_u32_e32 v75, 0x63, v166
	s_and_b64 s[18:19], s[76:77], vcc
	v_cmp_gt_u32_e32 vcc, s83, v75
	v_add_u32_e32 v106, 0x62, v166
	s_and_b64 s[20:21], s[76:77], vcc
	v_cmp_gt_u32_e32 vcc, s83, v106
	v_add_u32_e32 v116, 0x61, v166
	s_and_b64 s[22:23], s[76:77], vcc
	v_cmp_gt_u32_e32 vcc, s83, v116
	v_add_u32_e32 v117, 0x60, v166
	s_and_b64 s[24:25], s[76:77], vcc
	v_cmp_gt_u32_e32 vcc, s83, v117
	v_add_u32_e32 v117, 0x53, v166
	s_and_b64 s[26:27], s[76:77], vcc
	v_cmp_gt_u32_e32 vcc, s83, v117
	v_add_u32_e32 v117, 0x52, v166
	v_mul_f32_e32 v68, 0x3e38aa3b, v128
	v_mul_f32_e32 v69, 0x3e38aa3b, v129
	s_and_b64 s[28:29], s[76:77], vcc
	v_cmp_gt_u32_e32 vcc, s83, v117
	v_add_u32_e32 v117, 0x51, v166
	v_cndmask_b32_e64 v68, v68, v182, s[12:13]
	v_cndmask_b32_e64 v69, v69, v182, s[14:15]
	v_mul_f32_e32 v71, 0x3e38aa3b, v130
	v_mul_f32_e32 v72, 0x3e38aa3b, v131
	s_and_b64 s[30:31], s[76:77], vcc
	v_cmp_gt_u32_e32 vcc, s83, v117
	v_add_u32_e32 v117, 0x50, v166
	v_max3_f32 v70, v68, s71, v69
	v_cndmask_b32_e64 v71, v71, v182, s[16:17]
	v_cndmask_b32_e64 v72, v72, v182, s[18:19]
	v_mul_f32_e32 v74, 0x3e38aa3b, v132
	v_mul_f32_e32 v75, 0x3e38aa3b, v133
	s_and_b64 s[34:35], s[76:77], vcc
	v_cmp_gt_u32_e32 vcc, s83, v117
	v_add_u32_e32 v117, 0x43, v166
	v_max3_f32 v70, v70, v71, v72
	v_cndmask_b32_e64 v74, v74, v182, s[20:21]
	v_cndmask_b32_e64 v75, v75, v182, s[22:23]
	v_mul_f32_e32 v106, 0x3e38aa3b, v134
	v_mul_f32_e32 v116, 0x3e38aa3b, v135
	s_and_b64 s[36:37], s[76:77], vcc
	v_cmp_gt_u32_e32 vcc, s83, v117
	v_add_u32_e32 v117, 0x42, v166
	v_max3_f32 v70, v70, v74, v75
	v_cndmask_b32_e64 v106, v106, v182, s[24:25]
	v_cndmask_b32_e64 v116, v116, v182, s[26:27]
	v_mul_f32_e32 v108, 0x3e38aa3b, v108
	v_mul_f32_e32 v109, 0x3e38aa3b, v109
	v_cmp_gt_u32_e64 s[6:7], s83, v117
	v_add_u32_e32 v117, 0x41, v166
	v_max3_f32 v70, v70, v106, v116
	v_cndmask_b32_e64 v108, v108, v182, s[28:29]
	v_cndmask_b32_e64 v109, v109, v182, s[30:31]
	v_mul_f32_e32 v110, 0x3e38aa3b, v110
	v_mul_f32_e32 v111, 0x3e38aa3b, v111
	v_cmp_gt_u32_e64 s[8:9], s83, v117
	v_add_u32_e32 v117, 64, v166
	v_max3_f32 v70, v70, v108, v109
	v_cndmask_b32_e64 v110, v110, v182, s[34:35]
	v_cndmask_b32_e64 v111, v111, v182, s[36:37]
	v_mul_f32_e32 v112, 0x3e38aa3b, v112
	s_and_b64 vcc, s[76:77], vcc
	v_mul_f32_e32 v113, 0x3e38aa3b, v113
	s_and_b64 s[6:7], s[76:77], s[6:7]
	v_cmp_gt_u32_e64 s[10:11], s83, v117
	v_max3_f32 v70, v70, v110, v111
	v_cndmask_b32_e32 v112, v112, v182, vcc
	v_cndmask_b32_e64 v113, v113, v182, s[6:7]
	v_mul_f32_e32 v114, 0x3e38aa3b, v114
	s_and_b64 s[8:9], s[76:77], s[8:9]
	v_mul_f32_e32 v115, 0x3e38aa3b, v115
	s_and_b64 s[10:11], s[76:77], s[10:11]
	v_max3_f32 v70, v70, v112, v113
	v_cndmask_b32_e64 v114, v114, v182, s[8:9]
	v_cndmask_b32_e64 v118, v115, v182, s[10:11]
	v_max3_f32 v70, v70, v114, v118
	v_mov_b32_e32 v115, v70
	s_nop 1
	v_permlane16_swap_b32_e32 v70, v115
	v_max_f32_e32 v115, v115, v115
	v_max_f32_e32 v70, v70, v70
	v_max_f32_e32 v70, v70, v115
	v_mov_b32_e32 v115, v70
	s_nop 1
	v_permlane32_swap_b32_e32 v70, v115
	v_max3_f32 v140, v73, v70, v115
	v_sub_f32_e32 v68, v68, v140
	v_exp_f32_e32 v139, v68
	v_sub_f32_e32 v68, v69, v140
	v_exp_f32_e32 v137, v68
	v_sub_f32_e32 v68, v71, v140
	v_exp_f32_e32 v135, v68
	v_sub_f32_e32 v68, v72, v140
	v_exp_f32_e32 v133, v68
	v_sub_f32_e32 v68, v74, v140
	v_exp_f32_e32 v131, v68
	v_sub_f32_e32 v68, v75, v140
	v_exp_f32_e32 v129, v68
	v_sub_f32_e32 v68, v106, v140
	v_exp_f32_e32 v127, v68
	v_sub_f32_e32 v68, v116, v140
	v_exp_f32_e32 v125, v68
	v_sub_f32_e32 v68, v108, v140
	v_add_u32_e32 v108, 0x83, v166
	v_cmp_gt_u32_e64 s[40:41], s83, v108
	v_mul_f32_e32 v76, 0x3e38aa3b, v76
	s_and_b64 s[40:41], s[76:77], s[40:41]
	v_add_u32_e32 v108, 0x82, v166
	v_exp_f32_e32 v123, v68
	v_sub_f32_e32 v68, v109, v140
	v_cndmask_b32_e64 v76, v76, v182, s[40:41]
	v_cmp_gt_u32_e64 s[40:41], s83, v108
	v_exp_f32_e32 v121, v68
	v_sub_f32_e32 v68, v110, v140
	v_mul_f32_e32 v77, 0x3e38aa3b, v77
	s_and_b64 s[40:41], s[76:77], s[40:41]
	v_add_u32_e32 v110, 0x81, v166
	v_cndmask_b32_e64 v77, v77, v182, s[40:41]
	v_cmp_gt_u32_e64 s[40:41], s83, v110
	v_mul_f32_e32 v78, 0x3e38aa3b, v78
	s_and_b64 s[40:41], s[76:77], s[40:41]
	v_cndmask_b32_e64 v110, v78, v182, s[40:41]
	v_mul_f32_e32 v78, 0x3e38aa3b, v79
	v_add_u32_e32 v79, 0x80, v166
	v_cmp_gt_u32_e64 s[40:41], s83, v79
	s_and_b64 s[40:41], s[76:77], s[40:41]
	v_max3_f32 v108, v76, s71, v77
	v_cndmask_b32_e64 v79, v78, v182, s[40:41]
	v_mul_f32_e32 v80, 0x3e38aa3b, v80
	v_mul_f32_e32 v81, 0x3e38aa3b, v81
	v_exp_f32_e32 v119, v68
	v_sub_f32_e32 v68, v111, v140
	v_max3_f32 v78, v108, v110, v79
	v_cndmask_b32_e64 v80, v80, v182, s[12:13]
	v_cndmask_b32_e64 v81, v81, v182, s[14:15]
	v_mul_f32_e32 v82, 0x3e38aa3b, v82
	v_mul_f32_e32 v83, 0x3e38aa3b, v83
	v_exp_f32_e32 v115, v68
	v_sub_f32_e32 v68, v112, v140
	v_max3_f32 v78, v78, v80, v81
	v_cndmask_b32_e64 v82, v82, v182, s[16:17]
	v_cndmask_b32_e64 v83, v83, v182, s[18:19]
	v_mul_f32_e32 v84, 0x3e38aa3b, v84
	v_mul_f32_e32 v85, 0x3e38aa3b, v85
	v_exp_f32_e32 v111, v68
	v_sub_f32_e32 v68, v113, v140
	v_max3_f32 v78, v78, v82, v83
	v_cndmask_b32_e64 v84, v84, v182, s[20:21]
	v_cndmask_b32_e64 v85, v85, v182, s[22:23]
	v_mul_f32_e32 v86, 0x3e38aa3b, v86
	v_mul_f32_e32 v87, 0x3e38aa3b, v87
	v_exp_f32_e32 v109, v68
	v_sub_f32_e32 v68, v114, v140
	v_max3_f32 v78, v78, v84, v85
	v_cndmask_b32_e64 v86, v86, v182, s[24:25]
	v_cndmask_b32_e64 v87, v87, v182, s[26:27]
	v_mul_f32_e32 v108, 0x3e38aa3b, v142
	v_mul_f32_e32 v112, 0x3e38aa3b, v143
	v_mul_f32_e32 v114, 0x3e38aa3b, v144
	v_max3_f32 v78, v78, v86, v87
	v_cndmask_b32_e64 v108, v108, v182, s[28:29]
	v_cndmask_b32_e64 v112, v112, v182, s[30:31]
	v_cndmask_b32_e64 v116, v114, v182, s[34:35]
	v_mul_f32_e32 v114, 0x3e38aa3b, v145
	v_max3_f32 v78, v78, v108, v112
	v_cndmask_b32_e64 v141, v114, v182, s[36:37]
	v_max3_f32 v78, v78, v116, v141
	v_mov_b32_e32 v114, v78
	s_nop 1
	v_permlane16_swap_b32_e32 v78, v114
	v_max_f32_e32 v114, v114, v114
	v_max_f32_e32 v78, v78, v78
	v_max_f32_e32 v78, v78, v114
	v_mov_b32_e32 v114, v78
	s_nop 1
	v_permlane32_swap_b32_e32 v78, v114
	v_max3_f32 v78, v167, v78, v114
	v_sub_f32_e32 v76, v76, v78
	v_exp_f32_e32 v138, v76
	v_sub_f32_e32 v76, v77, v78
	v_exp_f32_e32 v136, v76
	v_sub_f32_e32 v76, v110, v78
	v_exp_f32_e32 v134, v76
	v_sub_f32_e32 v76, v79, v78
	v_exp_f32_e32 v132, v76
	v_sub_f32_e32 v76, v80, v78
	v_exp_f32_e32 v130, v76
	v_sub_f32_e32 v76, v81, v78
	v_exp_f32_e32 v128, v76
	v_sub_f32_e32 v76, v82, v78
	v_exp_f32_e32 v126, v76
	v_sub_f32_e32 v76, v83, v78
	v_exp_f32_e32 v124, v76
	v_sub_f32_e32 v76, v84, v78
	v_exp_f32_e32 v122, v76
	v_sub_f32_e32 v76, v85, v78
	v_exp_f32_e32 v120, v76
	v_sub_f32_e32 v76, v86, v78
	v_exp_f32_e32 v117, v68
	v_sub_f32_e32 v68, v118, v140
	v_exp_f32_e32 v118, v76
	v_sub_f32_e32 v76, v87, v78
	v_exp_f32_e32 v114, v76
	v_sub_f32_e32 v76, v108, v78
	v_sub_f32_e32 v77, v116, v78
	v_sub_f32_e32 v70, v73, v140
	v_sub_f32_e32 v142, v167, v78
	v_exp_f32_e32 v110, v76
	v_sub_f32_e32 v76, v112, v78
	v_exp_f32_e32 v116, v77
	v_sub_f32_e32 v77, v141, v78
	v_exp_f32_e32 v106, v70
	v_exp_f32_e32 v113, v68
	v_exp_f32_e32 v108, v76
	v_exp_f32_e32 v76, v142
	v_exp_f32_e32 v112, v77
	v_pk_mul_f32 v[58:59], v[58:59], v[106:107] op_sel_hi:[1,0]
	v_pk_mul_f32 v[56:57], v[56:57], v[106:107] op_sel_hi:[1,0]
	v_pk_mul_f32 v[54:55], v[54:55], v[106:107] op_sel_hi:[1,0]
	v_pk_mul_f32 v[52:53], v[52:53], v[106:107] op_sel_hi:[1,0]
	v_pk_mul_f32 v[62:63], v[62:63], v[106:107] op_sel_hi:[1,0]
	v_pk_mul_f32 v[60:61], v[60:61], v[106:107] op_sel_hi:[1,0]
	v_pk_mul_f32 v[70:71], v[66:67], v[106:107] op_sel_hi:[1,0]
	v_pk_mul_f32 v[68:69], v[64:65], v[106:107] op_sel_hi:[1,0]
	v_cvt_pk_bf16_f32 v72, v139, v137
	v_cvt_pk_bf16_f32 v73, v135, v133
	v_cvt_pk_bf16_f32 v74, v131, v129
	v_cvt_pk_bf16_f32 v75, v127, v125
	v_cvt_pk_bf16_f32 v64, v123, v121
	v_cvt_pk_bf16_f32 v65, v119, v115
	v_cvt_pk_bf16_f32 v66, v111, v109
	v_cvt_pk_bf16_f32 v67, v117, v113
	v_pk_mul_f32 v[42:43], v[42:43], v[76:77] op_sel_hi:[1,0]
	v_pk_mul_f32 v[40:41], v[40:41], v[76:77] op_sel_hi:[1,0]
	v_pk_mul_f32 v[38:39], v[38:39], v[76:77] op_sel_hi:[1,0]
	v_pk_mul_f32 v[36:37], v[36:37], v[76:77] op_sel_hi:[1,0]
	v_pk_mul_f32 v[46:47], v[46:47], v[76:77] op_sel_hi:[1,0]
	v_pk_mul_f32 v[44:45], v[44:45], v[76:77] op_sel_hi:[1,0]
	v_pk_mul_f32 v[50:51], v[50:51], v[76:77] op_sel_hi:[1,0]
	v_pk_mul_f32 v[48:49], v[48:49], v[76:77] op_sel_hi:[1,0]
	v_cvt_pk_bf16_f32 v80, v138, v136
	v_cvt_pk_bf16_f32 v81, v134, v132
	v_cvt_pk_bf16_f32 v82, v130, v128
	v_cvt_pk_bf16_f32 v83, v126, v124
	v_cvt_pk_bf16_f32 v84, v122, v120
	v_cvt_pk_bf16_f32 v85, v118, v114
	v_cvt_pk_bf16_f32 v86, v110, v108
	v_cvt_pk_bf16_f32 v87, v116, v112
	s_setprio 1
	v_add3_u32 v77, s78, v164, v165
	ds_read_b64_tr_b16 v[206:207], v77 offset:20992
	ds_read_b64_tr_b16 v[204:205], v77 offset:18432
	ds_read_b64_tr_b16 v[208:209], v77 offset:18464
	ds_read_b64_tr_b16 v[210:211], v77 offset:21024
	ds_read_b64_tr_b16 v[212:213], v77 offset:23552
	ds_read_b64_tr_b16 v[214:215], v77 offset:26112
	ds_read_b64_tr_b16 v[216:217], v77 offset:23584
	ds_read_b64_tr_b16 v[218:219], v77 offset:26144
	ds_read_b64_tr_b16 v[220:221], v77 offset:18496
	ds_read_b64_tr_b16 v[222:223], v77 offset:21056
	ds_read_b64_tr_b16 v[224:225], v77 offset:23616
	ds_read_b64_tr_b16 v[226:227], v77 offset:26176
	ds_read_b64_tr_b16 v[228:229], v77 offset:18528
	ds_read_b64_tr_b16 v[230:231], v77 offset:21088
	ds_read_b64_tr_b16 v[232:233], v77 offset:23648
	ds_read_b64_tr_b16 v[234:235], v77 offset:26208
	s_waitcnt lgkmcnt(14)
	v_mfma_f32_16x16x32_bf16 v[56:59], v[204:207], v[72:75], v[56:59]
	v_mfma_f32_16x16x32_bf16 v[40:43], v[204:207], v[80:83], v[40:43]
	s_waitcnt lgkmcnt(10)
	v_mfma_f32_16x16x32_bf16 v[56:59], v[212:215], v[64:67], v[56:59]
	v_mfma_f32_16x16x32_bf16 v[40:43], v[212:215], v[84:87], v[40:43]
	v_mfma_f32_16x16x32_bf16 v[52:55], v[208:211], v[72:75], v[52:55]
	v_mfma_f32_16x16x32_bf16 v[36:39], v[208:211], v[80:83], v[36:39]
	s_waitcnt lgkmcnt(8)
	v_mfma_f32_16x16x32_bf16 v[52:55], v[216:219], v[64:67], v[52:55]
	v_mfma_f32_16x16x32_bf16 v[36:39], v[216:219], v[84:87], v[36:39]
	s_waitcnt lgkmcnt(6)
	v_mfma_f32_16x16x32_bf16 v[60:63], v[220:223], v[72:75], v[60:63]
	v_mfma_f32_16x16x32_bf16 v[44:47], v[220:223], v[80:83], v[44:47]
	s_waitcnt lgkmcnt(4)
	v_mfma_f32_16x16x32_bf16 v[60:63], v[224:227], v[64:67], v[60:63]
	v_mfma_f32_16x16x32_bf16 v[44:47], v[224:227], v[84:87], v[44:47]
	s_waitcnt lgkmcnt(2)
	v_mfma_f32_16x16x32_bf16 v[68:71], v[228:231], v[72:75], v[68:71]
	v_mfma_f32_16x16x32_bf16 v[48:51], v[228:231], v[80:83], v[48:51]
	s_waitcnt lgkmcnt(0)
	v_mfma_f32_16x16x32_bf16 v[64:67], v[232:235], v[64:67], v[68:71]
	v_mfma_f32_16x16x32_bf16 v[48:51], v[232:235], v[84:87], v[48:51]
	s_nop 3
	s_setprio 0
	s_setprio 1
	ds_read_b128 v[204:207], v88 offset:9216
	ds_read_b128 v[208:211], v88 offset:9280
	ds_read_b128 v[212:215], v88 offset:11520
	ds_read_b128 v[216:219], v88 offset:13824
	ds_read_b128 v[220:223], v88 offset:16128
	ds_read_b128 v[224:227], v88 offset:11584
	ds_read_b128 v[228:231], v88 offset:13888
	ds_read_b128 v[232:235], v88 offset:16192
	s_waitcnt lgkmcnt(7)
	v_mfma_f32_16x16x32_bf16 v[72:75], v[204:207], v[4:7], v[0:3]
	v_mfma_f32_16x16x32_bf16 v[68:71], v[204:207], v[12:15], v[0:3]
	s_waitcnt lgkmcnt(6)
	v_mfma_f32_16x16x32_bf16 v[168:171], v[208:211], v[16:19], v[68:71]
	v_mfma_f32_16x16x32_bf16 v[72:75], v[208:211], v[8:11], v[72:75]
	s_waitcnt lgkmcnt(5)
	v_mfma_f32_16x16x32_bf16 v[84:87], v[212:215], v[4:7], v[0:3]
	v_mfma_f32_16x16x32_bf16 v[80:83], v[212:215], v[12:15], v[0:3]
	s_waitcnt lgkmcnt(2)
	v_mfma_f32_16x16x32_bf16 v[84:87], v[224:227], v[8:11], v[84:87]
	v_mfma_f32_16x16x32_bf16 v[186:189], v[224:227], v[16:19], v[80:83]
	v_mfma_f32_16x16x32_bf16 v[146:149], v[216:219], v[4:7], v[0:3]
	v_mfma_f32_16x16x32_bf16 v[142:145], v[216:219], v[12:15], v[0:3]
	s_waitcnt lgkmcnt(1)
	v_mfma_f32_16x16x32_bf16 v[80:83], v[228:231], v[8:11], v[146:149]
	v_mfma_f32_16x16x32_bf16 v[190:193], v[228:231], v[16:19], v[142:145]
	v_mfma_f32_16x16x32_bf16 v[154:157], v[220:223], v[4:7], v[0:3]
	v_mfma_f32_16x16x32_bf16 v[150:153], v[220:223], v[12:15], v[0:3]
	s_waitcnt lgkmcnt(0)
	v_mfma_f32_16x16x32_bf16 v[142:145], v[232:235], v[8:11], v[154:157]
	v_mfma_f32_16x16x32_bf16 v[194:197], v[232:235], v[16:19], v[150:153]
	s_nop 0
	s_setprio 0
	v_mul_f32_e32 v68, 0x3e38aa3b, v72
	v_add_u32_e32 v69, 51, v166
	v_mul_f32_e32 v71, 0x3e38aa3b, v74
	v_add_u32_e32 v72, 49, v166
	v_add_u32_e32 v74, 35, v166
	v_cmp_gt_u32_e64 s[12:13], s83, v69
	v_mul_f32_e32 v69, 0x3e38aa3b, v73
	v_cmp_gt_u32_e64 s[16:17], s83, v72
	v_mul_f32_e32 v72, 0x3e38aa3b, v75
	v_add_u32_e32 v73, 48, v166
	v_cmp_gt_u32_e64 s[20:21], s83, v74
	v_add_u32_e32 v75, 34, v166
	v_cmp_gt_u32_e64 s[18:19], s83, v73
	v_mul_f32_e32 v73, 0x3e38aa3b, v84
	s_and_b64 s[20:21], s[76:77], s[20:21]
	v_cmp_gt_u32_e64 s[22:23], s83, v75
	v_add_u32_e32 v79, 33, v166
	v_cndmask_b32_e64 v74, v73, v182, s[20:21]
	v_mul_f32_e32 v73, 0x3e38aa3b, v85
	s_and_b64 s[22:23], s[76:77], s[22:23]
	v_cmp_gt_u32_e64 s[24:25], s83, v79
	v_add_u32_e32 v84, 32, v166
	v_cndmask_b32_e64 v75, v73, v182, s[22:23]
	v_mul_f32_e32 v73, 0x3e38aa3b, v86
	s_and_b64 s[24:25], s[76:77], s[24:25]
	v_cmp_gt_u32_e64 s[26:27], s83, v84
	v_cndmask_b32_e64 v79, v73, v182, s[24:25]
	v_mul_f32_e32 v73, 0x3e38aa3b, v87
	s_and_b64 s[26:27], s[76:77], s[26:27]
	v_cndmask_b32_e64 v84, v73, v182, s[26:27]
	v_mul_f32_e32 v73, 0x3e38aa3b, v80
	v_add_u32_e32 v80, 19, v166
	v_cmp_gt_u32_e64 s[28:29], s83, v80
	s_and_b64 s[28:29], s[76:77], s[28:29]
	v_add_u32_e32 v70, 50, v166
	v_cndmask_b32_e64 v80, v73, v182, s[28:29]
	v_mul_f32_e32 v73, 0x3e38aa3b, v81
	v_add_u32_e32 v81, 18, v166
	v_cmp_gt_u32_e64 s[30:31], s83, v81
	s_and_b64 s[30:31], s[76:77], s[30:31]
	v_cmp_gt_u32_e64 s[14:15], s83, v70
	v_cndmask_b32_e64 v81, v73, v182, s[30:31]
	v_mul_f32_e32 v73, 0x3e38aa3b, v82
	v_add_u32_e32 v82, 17, v166
	v_cmp_gt_u32_e64 s[34:35], s83, v82
	s_and_b64 s[34:35], s[76:77], s[34:35]
	v_add_u32_e32 v85, 3, v166
	v_cndmask_b32_e64 v82, v73, v182, s[34:35]
	v_mul_f32_e32 v73, 0x3e38aa3b, v83
	v_add_u32_e32 v83, 16, v166
	v_cmp_gt_u32_e64 s[36:37], s83, v83
	s_and_b64 s[12:13], s[76:77], s[12:13]
	s_and_b64 s[14:15], s[76:77], s[14:15]
	s_and_b64 s[36:37], s[76:77], s[36:37]
	v_cmp_gt_u32_e64 s[40:41], s83, v85
	v_cndmask_b32_e64 v68, v68, v182, s[12:13]
	v_cndmask_b32_e64 v69, v69, v182, s[14:15]
	s_and_b64 s[16:17], s[76:77], s[16:17]
	s_and_b64 s[18:19], s[76:77], s[18:19]
	v_cndmask_b32_e64 v83, v73, v182, s[36:37]
	v_mul_f32_e32 v73, 0x3e38aa3b, v142
	s_and_b64 s[40:41], s[76:77], s[40:41]
	v_add_u32_e32 v86, 2, v166
	v_max3_f32 v70, v68, s71, v69
	v_cndmask_b32_e64 v71, v71, v182, s[16:17]
	v_cndmask_b32_e64 v72, v72, v182, s[18:19]
	v_cndmask_b32_e64 v85, v73, v182, s[40:41]
	v_cmp_gt_u32_e64 s[40:41], s83, v86
	v_max3_f32 v70, v70, v71, v72
	v_mul_f32_e32 v73, 0x3e38aa3b, v143
	s_and_b64 s[40:41], s[76:77], s[40:41]
	v_add_u32_e32 v87, 1, v166
	v_max3_f32 v70, v70, v74, v75
	v_cndmask_b32_e64 v86, v73, v182, s[40:41]
	v_cmp_gt_u32_e64 s[40:41], s83, v87
	v_max3_f32 v70, v70, v79, v84
	v_mul_f32_e32 v73, 0x3e38aa3b, v144
	s_and_b64 s[40:41], s[76:77], s[40:41]
	v_max3_f32 v70, v70, v80, v81
	v_cndmask_b32_e64 v88, v73, v182, s[40:41]
	v_cmp_gt_u32_e64 s[40:41], s83, v166
	v_max3_f32 v70, v70, v82, v83
	v_mul_f32_e32 v73, 0x3e38aa3b, v145
	s_and_b64 s[40:41], s[76:77], s[40:41]
	v_max3_f32 v70, v70, v85, v86
	v_cndmask_b32_e64 v142, v73, v182, s[40:41]
	v_max3_f32 v70, v70, v88, v142
	v_mov_b32_e32 v73, v70
	s_nop 1
	v_permlane16_swap_b32_e32 v70, v73
	v_max_f32_e32 v73, v73, v73
	v_max_f32_e32 v70, v70, v70
	v_max_f32_e32 v70, v70, v73
	v_mov_b32_e32 v73, v70
	s_nop 1
	v_permlane32_swap_b32_e32 v70, v73
	v_max3_f32 v73, v140, v70, v73
	v_sub_f32_e32 v68, v68, v73
	v_exp_f32_e32 v159, v68
	v_sub_f32_e32 v68, v69, v73
	v_exp_f32_e32 v157, v68
	v_sub_f32_e32 v68, v71, v73
	v_exp_f32_e32 v155, v68
	v_sub_f32_e32 v68, v72, v73
	v_exp_f32_e32 v153, v68
	v_sub_f32_e32 v68, v74, v73
	v_exp_f32_e32 v151, v68
	v_sub_f32_e32 v68, v75, v73
	v_exp_f32_e32 v149, v68
	v_sub_f32_e32 v68, v79, v73
	v_exp_f32_e32 v147, v68
	v_sub_f32_e32 v68, v84, v73
	v_exp_f32_e32 v145, v68
	v_sub_f32_e32 v68, v80, v73
	v_exp_f32_e32 v143, v68
	v_sub_f32_e32 v68, v81, v73
	v_exp_f32_e32 v141, v68
	v_sub_f32_e32 v68, v82, v73
	v_sub_f32_e32 v70, v140, v73
	v_exp_f32_e32 v87, v68
	v_sub_f32_e32 v68, v83, v73
	v_exp_f32_e32 v83, v68
	v_sub_f32_e32 v68, v85, v73
	v_exp_f32_e32 v72, v70
	v_exp_f32_e32 v79, v68
	v_sub_f32_e32 v68, v86, v73
	v_exp_f32_e32 v75, v68
	v_sub_f32_e32 v68, v88, v73
	v_exp_f32_e32 v85, v68
	v_sub_f32_e32 v68, v142, v73
	v_exp_f32_e32 v81, v68
	v_pk_mul_f32 v[68:69], v[64:65], v[72:73] op_sel_hi:[1,0]
	v_mul_f32_e32 v64, 0x3e38aa3b, v168
	v_cndmask_b32_e32 v74, v64, v182, vcc
	v_mul_f32_e32 v64, 0x3e38aa3b, v169
	v_cndmask_b32_e64 v80, v64, v182, s[6:7]
	v_mul_f32_e32 v64, 0x3e38aa3b, v170
	v_cndmask_b32_e64 v82, v64, v182, s[8:9]
	v_mul_f32_e32 v64, 0x3e38aa3b, v171
	v_cndmask_b32_e64 v84, v64, v182, s[10:11]
	v_mul_f32_e32 v64, 0x3e38aa3b, v186
	v_cndmask_b32_e64 v86, v64, v182, s[12:13]
	v_mul_f32_e32 v64, 0x3e38aa3b, v187
	v_cndmask_b32_e64 v88, v64, v182, s[14:15]
	v_mul_f32_e32 v64, 0x3e38aa3b, v188
	v_cndmask_b32_e64 v140, v64, v182, s[16:17]
	v_mul_f32_e32 v64, 0x3e38aa3b, v189
	v_cndmask_b32_e64 v142, v64, v182, s[18:19]
	v_mul_f32_e32 v64, 0x3e38aa3b, v190
	v_cndmask_b32_e64 v160, v64, v182, s[20:21]
	v_mul_f32_e32 v64, 0x3e38aa3b, v191
	v_cndmask_b32_e64 v161, v64, v182, s[22:23]
	v_mul_f32_e32 v64, 0x3e38aa3b, v192
	v_cndmask_b32_e64 v172, v64, v182, s[24:25]
	v_mul_f32_e32 v64, 0x3e38aa3b, v193
	v_cndmask_b32_e64 v173, v64, v182, s[26:27]
	v_mul_f32_e32 v64, 0x3e38aa3b, v194
	v_cndmask_b32_e64 v185, v64, v182, s[28:29]
	v_mul_f32_e32 v64, 0x3e38aa3b, v195
	v_cndmask_b32_e64 v186, v64, v182, s[30:31]
	v_mul_f32_e32 v64, 0x3e38aa3b, v196
	v_cndmask_b32_e64 v187, v64, v182, s[34:35]
	v_mul_f32_e32 v64, 0x3e38aa3b, v197
	v_cndmask_b32_e64 v188, v64, v182, s[36:37]
	v_max3_f32 v64, v74, s71, v80
	v_max3_f32 v64, v64, v82, v84
	v_max3_f32 v64, v64, v86, v88
	v_max3_f32 v64, v64, v140, v142
	v_max3_f32 v64, v64, v160, v161
	v_max3_f32 v64, v64, v172, v173
	v_max3_f32 v144, v64, v185, v186
	v_max3_f32 v144, v144, v187, v188
	v_mov_b32_e32 v146, v144
	s_nop 1
	v_permlane16_swap_b32_e32 v144, v146
	v_max_f32_e32 v146, v146, v146
	v_max_f32_e32 v144, v144, v144
	v_max_f32_e32 v144, v144, v146
	v_mov_b32_e32 v146, v144
	s_nop 1
	v_permlane32_swap_b32_e32 v144, v146
	v_max3_f32 v167, v78, v144, v146
	v_sub_f32_e32 v74, v74, v167
	v_exp_f32_e32 v158, v74
	v_sub_f32_e32 v74, v80, v167
	v_exp_f32_e32 v156, v74
	v_sub_f32_e32 v74, v82, v167
	v_exp_f32_e32 v154, v74
	v_sub_f32_e32 v74, v84, v167
	v_exp_f32_e32 v152, v74
	v_sub_f32_e32 v74, v86, v167
	v_exp_f32_e32 v150, v74
	v_sub_f32_e32 v74, v88, v167
	v_exp_f32_e32 v148, v74
	v_sub_f32_e32 v74, v140, v167
	v_exp_f32_e32 v146, v74
	v_sub_f32_e32 v74, v142, v167
	v_exp_f32_e32 v144, v74
	v_sub_f32_e32 v74, v160, v167
	v_exp_f32_e32 v142, v74
	v_sub_f32_e32 v74, v161, v167
	v_exp_f32_e32 v140, v74
	v_sub_f32_e32 v74, v172, v167
	v_exp_f32_e32 v86, v74
	v_sub_f32_e32 v74, v173, v167
	v_sub_f32_e32 v189, v78, v167
	v_exp_f32_e32 v82, v74
	v_sub_f32_e32 v74, v185, v167
	v_sub_f32_e32 v80, v187, v167
	v_exp_f32_e32 v78, v74
	v_sub_f32_e32 v74, v186, v167
	v_exp_f32_e32 v160, v189
	v_exp_f32_e32 v84, v80
	v_sub_f32_e32 v80, v188, v167
	v_exp_f32_e32 v74, v74
	v_exp_f32_e32 v80, v80
	v_pk_mul_f32 v[58:59], v[58:59], v[72:73] op_sel_hi:[1,0]
	v_pk_mul_f32 v[56:57], v[56:57], v[72:73] op_sel_hi:[1,0]
	v_pk_mul_f32 v[54:55], v[54:55], v[72:73] op_sel_hi:[1,0]
	v_pk_mul_f32 v[52:53], v[52:53], v[72:73] op_sel_hi:[1,0]
	v_pk_mul_f32 v[62:63], v[62:63], v[72:73] op_sel_hi:[1,0]
	v_pk_mul_f32 v[60:61], v[60:61], v[72:73] op_sel_hi:[1,0]
	v_pk_mul_f32 v[70:71], v[66:67], v[72:73] op_sel_hi:[1,0]
	v_cvt_pk_bf16_f32 v64, v143, v141
	v_cvt_pk_bf16_f32 v65, v87, v83
	v_cvt_pk_bf16_f32 v66, v79, v75
	v_cvt_pk_bf16_f32 v67, v85, v81
	v_pk_mul_f32 v[42:43], v[42:43], v[160:161] op_sel_hi:[1,0]
	v_pk_mul_f32 v[40:41], v[40:41], v[160:161] op_sel_hi:[1,0]
	v_pk_mul_f32 v[38:39], v[38:39], v[160:161] op_sel_hi:[1,0]
	v_pk_mul_f32 v[36:37], v[36:37], v[160:161] op_sel_hi:[1,0]
	v_pk_mul_f32 v[46:47], v[46:47], v[160:161] op_sel_hi:[1,0]
	v_pk_mul_f32 v[44:45], v[44:45], v[160:161] op_sel_hi:[1,0]
	v_pk_mul_f32 v[50:51], v[50:51], v[160:161] op_sel_hi:[1,0]
	v_pk_mul_f32 v[48:49], v[48:49], v[160:161] op_sel_hi:[1,0]
	v_cvt_pk_bf16_f32 v168, v159, v157
	v_cvt_pk_bf16_f32 v169, v155, v153
	v_cvt_pk_bf16_f32 v170, v151, v149
	v_cvt_pk_bf16_f32 v171, v147, v145
	v_cvt_pk_bf16_f32 v186, v158, v156
	v_cvt_pk_bf16_f32 v187, v154, v152
	v_cvt_pk_bf16_f32 v188, v150, v148
	v_cvt_pk_bf16_f32 v189, v146, v144
	v_cvt_pk_bf16_f32 v190, v142, v140
	v_cvt_pk_bf16_f32 v191, v86, v82
	v_cvt_pk_bf16_f32 v192, v78, v74
	v_cvt_pk_bf16_f32 v193, v84, v80
	s_setprio 1
	ds_read_b64_tr_b16 v[206:207], v77 offset:31232
	ds_read_b64_tr_b16 v[204:205], v77 offset:28672
	ds_read_b64_tr_b16 v[208:209], v77 offset:28704
	ds_read_b64_tr_b16 v[210:211], v77 offset:31264
	ds_read_b64_tr_b16 v[212:213], v77 offset:33792
	ds_read_b64_tr_b16 v[214:215], v77 offset:36352
	ds_read_b64_tr_b16 v[216:217], v77 offset:33824
	ds_read_b64_tr_b16 v[218:219], v77 offset:36384
	ds_read_b64_tr_b16 v[220:221], v77 offset:28736
	ds_read_b64_tr_b16 v[222:223], v77 offset:31296
	ds_read_b64_tr_b16 v[224:225], v77 offset:33856
	ds_read_b64_tr_b16 v[226:227], v77 offset:36416
	ds_read_b64_tr_b16 v[228:229], v77 offset:28768
	ds_read_b64_tr_b16 v[230:231], v77 offset:31328
	ds_read_b64_tr_b16 v[232:233], v77 offset:33888
	ds_read_b64_tr_b16 v[234:235], v77 offset:36448
	s_waitcnt lgkmcnt(14)
	v_mfma_f32_16x16x32_bf16 v[56:59], v[204:207], v[168:171], v[56:59]
	v_mfma_f32_16x16x32_bf16 v[40:43], v[204:207], v[186:189], v[40:43]
	s_waitcnt lgkmcnt(10)
	v_mfma_f32_16x16x32_bf16 v[56:59], v[212:215], v[64:67], v[56:59]
	v_mfma_f32_16x16x32_bf16 v[40:43], v[212:215], v[190:193], v[40:43]
	v_mfma_f32_16x16x32_bf16 v[52:55], v[208:211], v[168:171], v[52:55]
	v_mfma_f32_16x16x32_bf16 v[36:39], v[208:211], v[186:189], v[36:39]
	s_waitcnt lgkmcnt(8)
	v_mfma_f32_16x16x32_bf16 v[52:55], v[216:219], v[64:67], v[52:55]
	v_mfma_f32_16x16x32_bf16 v[36:39], v[216:219], v[190:193], v[36:39]
	s_waitcnt lgkmcnt(6)
	v_mfma_f32_16x16x32_bf16 v[60:63], v[220:223], v[168:171], v[60:63]
	v_mfma_f32_16x16x32_bf16 v[44:47], v[220:223], v[186:189], v[44:47]
	s_waitcnt lgkmcnt(4)
	v_mfma_f32_16x16x32_bf16 v[60:63], v[224:227], v[64:67], v[60:63]
	v_mfma_f32_16x16x32_bf16 v[44:47], v[224:227], v[190:193], v[44:47]
	s_waitcnt lgkmcnt(2)
	v_mfma_f32_16x16x32_bf16 v[68:71], v[228:231], v[168:171], v[68:71]
	v_mfma_f32_16x16x32_bf16 v[48:51], v[228:231], v[186:189], v[48:51]
	s_waitcnt lgkmcnt(0)
	v_mfma_f32_16x16x32_bf16 v[64:67], v[232:235], v[64:67], v[68:71]
	v_mfma_f32_16x16x32_bf16 v[48:51], v[232:235], v[190:193], v[48:51]
	s_nop 3
	s_setprio 0
	s_add_i32 s12, s33, 1
	s_cmp_ge_i32 s12, s44
	s_cbranch_scc1 .LBB0_1303
	s_bitcmp1_b32 s12, 0
	s_cselect_b32 s6, 0x9800, 0
	v_add3_u32 v71, s6, v99, v98
	v_add3_u32 v68, s6, v162, v98
	v_add3_u32 v69, s6, v107, v98
	v_add3_u32 v70, s6, v103, v98
	s_waitcnt vmcnt(0)
	ds_write_b128 v71, v[20:23]
	ds_write_b128 v70, v[24:27]
	ds_write_b128 v69, v[28:31] offset:18432
	ds_write_b128 v68, v[32:35] offset:18432

.LBB0_1319:
	s_or_b64 exec, exec, s[6:7]
	s_add_i32 s8, s10, 0xffffff00
	s_ashr_i32 s9, s8, 31
	s_lshl_b64 s[6:7], s[8:9], 9
	v_readlane_b32 s20, v252, 19
	v_readlane_b32 s21, v252, 20
	s_add_u32 s14, s20, s6
	s_addc_u32 s15, s21, s7
	s_add_u32 s16, s14, 0x20000
	s_addc_u32 s17, s15, 0
	s_mul_hi_i32 s7, s8, 0x3000
	s_mul_i32 s6, s8, 0x3000
	s_lshl_b64 s[12:13], s[6:7], 1
	v_readlane_b32 s20, v252, 17
	v_readlane_b32 s21, v252, 18
	s_add_u32 s12, s20, s12
	s_addc_u32 s13, s21, s13
	s_movk_i32 s11, 0xff
	s_movk_i32 s20, 0x100
	v_sub_u32_e32 v10, 0x11f, v8
	v_add_u32_e32 v11, -1, v10
	v_med3_i32 v20, v10, 0, s11
	v_med3_i32 v21, v11, 0, s11
	v_lshlrev_b32_e32 v20, 1, v20
	v_lshlrev_b32_e32 v21, 1, v21
	global_load_ushort v30, v20, s[14:15]
	global_load_ushort v31, v21, s[14:15]
	global_load_ushort v32, v20, s[16:17]
	global_load_ushort v33, v21, s[16:17]
	v_lshlrev_b32_e32 v6, 4, v8
	global_load_dwordx4 v[70:73], v6, s[12:13]
	v_lshrrev_b32_e32 v4, 5, v8
	v_lshl_add_u32 v50, v8, 4, v184
	v_lshl_add_u32 v50, v4, 10, v50
	v_lshlrev_b32_e32 v51, 1, v8
	s_waitcnt vmcnt(1)
	v_cmp_gt_u32_e32 vcc, 0x100, v10
	v_cmp_gt_u32_e64 s[18:19], s20, v11
	s_nop 1
	v_cndmask_b32_e32 v30, 0, v30, vcc
	v_cndmask_b32_e32 v32, 0, v32, vcc
	v_cndmask_b32_e64 v31, 0, v31, s[18:19]
	v_cndmask_b32_e64 v33, 0, v33, s[18:19]
	v_cmp_gt_u32_e32 vcc, 0x130, v8
	s_and_saveexec_b64 s[18:19], vcc
	ds_write_b16 v51, v30
	ds_write_b16 v51, v31 offset:608
	ds_write_b16 v51, v32 offset:1216
	ds_write_b16 v51, v33 offset:1824
	s_or_b64 exec, exec, s[18:19]
	s_waitcnt lgkmcnt(0)
	s_barrier
	s_waitcnt vmcnt(0)
	ds_write_b128 v50, v[70:73]
	s_mov_b64 s[8:9], exec

.LBB0_2968:
	s_bitcmp1_b32 s10, 0
	s_cselect_b32 s11, 0xb800, 0
	s_setprio 1
	v_or_b32_e32 v80, s11, v94
	v_add_u32_e32 v109, v80, v186
	ds_read_b128 v[220:223], v109
	ds_read_b128 v[224:227], v109 offset:64
	ds_read_b128 v[228:231], v109 offset:3328
	ds_read_b128 v[232:235], v109 offset:6656
	ds_read_b128 v[236:239], v109 offset:9984
	ds_read_b128 v[240:243], v109 offset:3392
	ds_read_b128 v[244:247], v109 offset:6720
	ds_read_b128 v[248:251], v109 offset:10048
	s_waitcnt lgkmcnt(7)
	v_mfma_f32_16x16x32_bf16 v[112:115], v[220:223], v[4:7], v[0:3]
	v_mfma_f32_16x16x32_bf16 v[82:85], v[220:223], v[16:19], v[0:3]
	ds_read_b128 v[220:223], v109 offset:128
	s_waitcnt lgkmcnt(7)
	v_mfma_f32_16x16x32_bf16 v[112:115], v[224:227], v[8:11], v[112:115]
	v_mfma_f32_16x16x32_bf16 v[82:85], v[224:227], v[20:23], v[82:85]
	ds_read_b128 v[224:227], v109 offset:3456
	s_waitcnt lgkmcnt(7)
	v_mfma_f32_16x16x32_bf16 v[120:123], v[228:231], v[4:7], v[0:3]
	v_mfma_f32_16x16x32_bf16 v[116:119], v[228:231], v[16:19], v[0:3]
	ds_read_b128 v[228:231], v109 offset:6784
	s_waitcnt lgkmcnt(5)
	v_mfma_f32_16x16x32_bf16 v[120:123], v[240:243], v[8:11], v[120:123]
	v_mfma_f32_16x16x32_bf16 v[116:119], v[240:243], v[20:23], v[116:119]
	ds_read_b128 v[240:243], v109 offset:10112
	v_mfma_f32_16x16x32_bf16 v[128:131], v[232:235], v[4:7], v[0:3]
	v_mfma_f32_16x16x32_bf16 v[124:127], v[232:235], v[16:19], v[0:3]
	s_waitcnt lgkmcnt(5)
	v_mfma_f32_16x16x32_bf16 v[128:131], v[244:247], v[8:11], v[128:131]
	v_mfma_f32_16x16x32_bf16 v[124:127], v[244:247], v[20:23], v[124:127]
	v_mfma_f32_16x16x32_bf16 v[136:139], v[236:239], v[4:7], v[0:3]
	v_mfma_f32_16x16x32_bf16 v[132:135], v[236:239], v[16:19], v[0:3]
	s_waitcnt lgkmcnt(4)
	v_mfma_f32_16x16x32_bf16 v[136:139], v[248:251], v[8:11], v[136:139]
	v_mfma_f32_16x16x32_bf16 v[132:135], v[248:251], v[20:23], v[132:135]
	s_waitcnt lgkmcnt(3)
	v_mfma_f32_16x16x32_bf16 v[148:151], v[220:223], v[24:27], v[82:85]
	s_waitcnt lgkmcnt(2)
	v_mfma_f32_16x16x32_bf16 v[120:123], v[224:227], v[12:15], v[120:123]
	v_mfma_f32_16x16x32_bf16 v[84:87], v[224:227], v[24:27], v[116:119]
	s_waitcnt lgkmcnt(1)
	v_mfma_f32_16x16x32_bf16 v[152:155], v[228:231], v[12:15], v[128:131]
	v_mfma_f32_16x16x32_bf16 v[156:159], v[228:231], v[24:27], v[124:127]
	v_mfma_f32_16x16x32_bf16 v[112:115], v[220:223], v[12:15], v[112:115]
	s_waitcnt lgkmcnt(0)
	v_mfma_f32_16x16x32_bf16 v[160:163], v[240:243], v[12:15], v[136:139]
	v_mfma_f32_16x16x32_bf16 v[164:167], v[240:243], v[24:27], v[132:135]
	s_nop 2
	s_setprio 0
	s_nop 3
	v_mul_f32_e32 v80, 0x3e16c740, v112
	v_mul_f32_e32 v82, 0x3e16c740, v113
	v_max3_f32 v80, v80, s68, v82
	v_mul_f32_e32 v82, 0x3e16c740, v114
	v_mul_f32_e32 v83, 0x3e16c740, v115
	v_max3_f32 v80, v80, v82, v83
	v_mul_f32_e32 v82, 0x3e16c740, v120
	v_mul_f32_e32 v83, 0x3e16c740, v121
	v_max3_f32 v80, v80, v82, v83
	v_mul_f32_e32 v82, 0x3e16c740, v122
	v_mul_f32_e32 v83, 0x3e16c740, v123
	v_max3_f32 v80, v80, v82, v83
	v_mul_f32_e32 v82, 0x3e16c740, v152
	v_mul_f32_e32 v83, 0x3e16c740, v153
	v_max3_f32 v80, v80, v82, v83
	v_mul_f32_e32 v82, 0x3e16c740, v154
	v_mul_f32_e32 v83, 0x3e16c740, v155
	v_max3_f32 v80, v80, v82, v83
	v_mul_f32_e32 v82, 0x3e16c740, v160
	v_mul_f32_e32 v83, 0x3e16c740, v161
	v_max3_f32 v80, v80, v82, v83
	v_mul_f32_e32 v82, 0x3e16c740, v162
	v_mul_f32_e32 v83, 0x3e16c740, v163
	v_max3_f32 v80, v80, v82, v83
	v_mov_b32_e32 v82, v80
	s_nop 1
	v_permlane16_swap_b32_e32 v80, v82
	v_max_f32_e32 v82, v82, v82
	v_max_f32_e32 v80, v80, v80
	v_max_f32_e32 v80, v80, v82
	v_mov_b32_e32 v82, v80
	s_nop 1
	v_permlane32_swap_b32_e32 v80, v82
	v_max3_f32 v144, v81, v80, v82
	v_sub_f32_e32 v80, v81, v144
	v_fma_f32 v81, v112, s38, -v144
	v_exp_f32_e32 v143, v81
	v_fma_f32 v81, v113, s38, -v144
	v_exp_f32_e32 v141, v81
	v_fma_f32 v81, v114, s38, -v144
	v_mul_f32_e32 v112, 0x3e16c740, v148
	v_mul_f32_e32 v114, 0x3e16c740, v149
	v_max3_f32 v112, v112, s68, v114
	v_mul_f32_e32 v114, 0x3e16c740, v150
	v_mul_f32_e32 v116, 0x3e16c740, v151
	v_max3_f32 v112, v112, v114, v116
	v_mul_f32_e32 v114, 0x3e16c740, v84
	v_mul_f32_e32 v116, 0x3e16c740, v85
	v_max3_f32 v112, v112, v114, v116
	v_mul_f32_e32 v114, 0x3e16c740, v86
	v_mul_f32_e32 v116, 0x3e16c740, v87
	v_max3_f32 v112, v112, v114, v116
	v_mul_f32_e32 v114, 0x3e16c740, v156
	v_mul_f32_e32 v116, 0x3e16c740, v157
	v_max3_f32 v112, v112, v114, v116
	v_mul_f32_e32 v114, 0x3e16c740, v158
	v_mul_f32_e32 v116, 0x3e16c740, v159
	v_max3_f32 v112, v112, v114, v116
	v_mul_f32_e32 v114, 0x3e16c740, v164
	v_mul_f32_e32 v116, 0x3e16c740, v165
	v_max3_f32 v112, v112, v114, v116
	v_mul_f32_e32 v114, 0x3e16c740, v166
	v_mul_f32_e32 v116, 0x3e16c740, v167
	v_max3_f32 v112, v112, v114, v116
	v_mov_b32_e32 v114, v112
	s_nop 1
	v_permlane16_swap_b32_e32 v112, v114
	v_max_f32_e32 v114, v114, v114
	v_max_f32_e32 v112, v112, v112
	v_max_f32_e32 v112, v112, v114
	v_mov_b32_e32 v114, v112
	v_exp_f32_e32 v139, v81
	v_fma_f32 v81, v115, s38, -v144
	v_permlane32_swap_b32_e32 v112, v114
	v_exp_f32_e32 v137, v81
	v_fma_f32 v81, v120, s38, -v144
	v_max3_f32 v146, v189, v112, v114
	v_exp_f32_e32 v135, v81
	v_fma_f32 v81, v121, s38, -v144
	v_fma_f32 v84, v84, s38, -v146
	v_exp_f32_e32 v133, v81
	v_fma_f32 v81, v122, s38, -v144
	v_exp_f32_e32 v134, v84
	v_fma_f32 v84, v85, s38, -v146
	v_exp_f32_e32 v131, v81
	v_fma_f32 v81, v123, s38, -v144
	v_exp_f32_e32 v132, v84
	v_fma_f32 v84, v86, s38, -v146
	v_exp_f32_e32 v129, v81
	v_fma_f32 v81, v152, s38, -v144
	v_exp_f32_e32 v130, v84
	v_fma_f32 v84, v87, s38, -v146
	v_exp_f32_e32 v127, v81
	v_fma_f32 v81, v153, s38, -v144
	v_exp_f32_e32 v128, v84
	v_fma_f32 v84, v156, s38, -v146
	v_exp_f32_e32 v125, v81
	v_fma_f32 v81, v154, s38, -v144
	v_exp_f32_e32 v126, v84
	v_fma_f32 v84, v157, s38, -v146
	v_exp_f32_e32 v123, v81
	v_fma_f32 v81, v155, s38, -v144
	v_fma_f32 v112, v148, s38, -v146
	v_exp_f32_e32 v124, v84
	v_fma_f32 v84, v158, s38, -v146
	v_exp_f32_e32 v119, v81
	v_fma_f32 v81, v160, s38, -v144
	v_exp_f32_e32 v142, v112
	v_fma_f32 v112, v149, s38, -v146
	v_exp_f32_e32 v122, v84
	v_fma_f32 v84, v159, s38, -v146
	v_exp_f32_e32 v115, v81
	v_fma_f32 v81, v161, s38, -v144
	v_exp_f32_e32 v140, v112
	v_fma_f32 v112, v150, s38, -v146
	v_exp_f32_e32 v118, v84
	v_fma_f32 v84, v164, s38, -v146
	v_fma_f32 v85, v166, s38, -v146
	v_exp_f32_e32 v113, v81
	v_fma_f32 v81, v162, s38, -v144
	v_exp_f32_e32 v110, v80
	v_fma_f32 v80, v163, s38, -v144
	v_sub_f32_e32 v116, v189, v146
	v_exp_f32_e32 v138, v112
	v_fma_f32 v112, v151, s38, -v146
	v_exp_f32_e32 v114, v84
	v_fma_f32 v84, v165, s38, -v146
	v_exp_f32_e32 v120, v85
	v_fma_f32 v85, v167, s38, -v146
	v_exp_f32_e32 v121, v81
	v_exp_f32_e32 v117, v80
	v_exp_f32_e32 v136, v112
	v_exp_f32_e32 v112, v84
	v_exp_f32_e32 v84, v116
	v_exp_f32_e32 v116, v85
	v_pk_mul_f32 v[70:71], v[70:71], v[110:111] op_sel_hi:[1,0]
	v_pk_mul_f32 v[68:69], v[68:69], v[110:111] op_sel_hi:[1,0]
	v_pk_mul_f32 v[66:67], v[66:67], v[110:111] op_sel_hi:[1,0]
	v_pk_mul_f32 v[64:65], v[64:65], v[110:111] op_sel_hi:[1,0]
	v_pk_mul_f32 v[74:75], v[74:75], v[110:111] op_sel_hi:[1,0]
	v_pk_mul_f32 v[72:73], v[72:73], v[110:111] op_sel_hi:[1,0]
	v_pk_mul_f32 v[82:83], v[78:79], v[110:111] op_sel_hi:[1,0]
	v_pk_mul_f32 v[80:81], v[76:77], v[110:111] op_sel_hi:[1,0]
	v_cvt_pk_bf16_f32 v152, v143, v141
	v_cvt_pk_bf16_f32 v153, v139, v137
	v_cvt_pk_bf16_f32 v154, v135, v133
	v_cvt_pk_bf16_f32 v155, v131, v129
	v_cvt_pk_bf16_f32 v76, v127, v125
	v_cvt_pk_bf16_f32 v77, v123, v119
	v_cvt_pk_bf16_f32 v78, v115, v113
	v_cvt_pk_bf16_f32 v79, v121, v117
	v_pk_mul_f32 v[54:55], v[54:55], v[84:85] op_sel_hi:[1,0]
	v_pk_mul_f32 v[52:53], v[52:53], v[84:85] op_sel_hi:[1,0]
	v_pk_mul_f32 v[50:51], v[50:51], v[84:85] op_sel_hi:[1,0]
	v_pk_mul_f32 v[48:49], v[48:49], v[84:85] op_sel_hi:[1,0]
	v_pk_mul_f32 v[58:59], v[58:59], v[84:85] op_sel_hi:[1,0]
	v_pk_mul_f32 v[56:57], v[56:57], v[84:85] op_sel_hi:[1,0]
	v_pk_mul_f32 v[62:63], v[62:63], v[84:85] op_sel_hi:[1,0]
	v_pk_mul_f32 v[60:61], v[60:61], v[84:85] op_sel_hi:[1,0]
	v_cvt_pk_bf16_f32 v148, v142, v140
	v_cvt_pk_bf16_f32 v149, v138, v136
	v_cvt_pk_bf16_f32 v150, v134, v132
	v_cvt_pk_bf16_f32 v151, v130, v128
	v_cvt_pk_bf16_f32 v156, v126, v124
	v_cvt_pk_bf16_f32 v157, v122, v118
	v_cvt_pk_bf16_f32 v158, v114, v112
	v_cvt_pk_bf16_f32 v159, v120, v116
	s_setprio 1
	v_add3_u32 v85, s11, v187, v188
	ds_read_b64_tr_b16 v[222:223], v85 offset:29184
	ds_read_b64_tr_b16 v[220:221], v85 offset:26624
	ds_read_b64_tr_b16 v[224:225], v85 offset:26656
	ds_read_b64_tr_b16 v[226:227], v85 offset:29216
	ds_read_b64_tr_b16 v[228:229], v85 offset:31744
	ds_read_b64_tr_b16 v[230:231], v85 offset:34304
	ds_read_b64_tr_b16 v[232:233], v85 offset:31776
	ds_read_b64_tr_b16 v[234:235], v85 offset:34336
	ds_read_b64_tr_b16 v[236:237], v85 offset:26688
	ds_read_b64_tr_b16 v[238:239], v85 offset:29248
	ds_read_b64_tr_b16 v[240:241], v85 offset:31808
	ds_read_b64_tr_b16 v[242:243], v85 offset:34368
	ds_read_b64_tr_b16 v[244:245], v85 offset:26720
	ds_read_b64_tr_b16 v[246:247], v85 offset:29280
	ds_read_b64_tr_b16 v[248:249], v85 offset:31840
	ds_read_b64_tr_b16 v[250:251], v85 offset:34400
	s_waitcnt lgkmcnt(14)
	v_mfma_f32_16x16x32_bf16 v[68:71], v[220:223], v[152:155], v[68:71]
	v_mfma_f32_16x16x32_bf16 v[52:55], v[220:223], v[148:151], v[52:55]
	s_waitcnt lgkmcnt(10)
	v_mfma_f32_16x16x32_bf16 v[68:71], v[228:231], v[76:79], v[68:71]
	v_mfma_f32_16x16x32_bf16 v[52:55], v[228:231], v[156:159], v[52:55]
	v_mfma_f32_16x16x32_bf16 v[64:67], v[224:227], v[152:155], v[64:67]
	v_mfma_f32_16x16x32_bf16 v[48:51], v[224:227], v[148:151], v[48:51]
	s_waitcnt lgkmcnt(8)
	v_mfma_f32_16x16x32_bf16 v[64:67], v[232:235], v[76:79], v[64:67]
	v_mfma_f32_16x16x32_bf16 v[48:51], v[232:235], v[156:159], v[48:51]
	s_waitcnt lgkmcnt(6)
	v_mfma_f32_16x16x32_bf16 v[72:75], v[236:239], v[152:155], v[72:75]
	v_mfma_f32_16x16x32_bf16 v[56:59], v[236:239], v[148:151], v[56:59]
	s_waitcnt lgkmcnt(4)
	v_mfma_f32_16x16x32_bf16 v[72:75], v[240:243], v[76:79], v[72:75]
	v_mfma_f32_16x16x32_bf16 v[56:59], v[240:243], v[156:159], v[56:59]
	s_waitcnt lgkmcnt(2)
	v_mfma_f32_16x16x32_bf16 v[60:63], v[244:247], v[148:151], v[60:63]
	v_mfma_f32_16x16x32_bf16 v[80:83], v[244:247], v[152:155], v[80:83]
	s_waitcnt lgkmcnt(0)
	v_mfma_f32_16x16x32_bf16 v[76:79], v[248:251], v[76:79], v[80:83]
	v_mfma_f32_16x16x32_bf16 v[60:63], v[248:251], v[156:159], v[60:63]
	s_nop 3
	s_setprio 0
	s_setprio 1
	ds_read_b128 v[220:223], v109 offset:13312
	ds_read_b128 v[224:227], v109 offset:13376
	ds_read_b128 v[228:231], v109 offset:16640
	ds_read_b128 v[232:235], v109 offset:19968
	ds_read_b128 v[236:239], v109 offset:23296
	ds_read_b128 v[240:243], v109 offset:16704
	ds_read_b128 v[244:247], v109 offset:20032
	ds_read_b128 v[248:251], v109 offset:23360
	s_waitcnt lgkmcnt(7)
	v_mfma_f32_16x16x32_bf16 v[148:151], v[220:223], v[4:7], v[0:3]
	v_mfma_f32_16x16x32_bf16 v[80:83], v[220:223], v[16:19], v[0:3]
	ds_read_b128 v[220:223], v109 offset:13440
	s_waitcnt lgkmcnt(7)
	v_mfma_f32_16x16x32_bf16 v[148:151], v[224:227], v[8:11], v[148:151]
	v_mfma_f32_16x16x32_bf16 v[80:83], v[224:227], v[20:23], v[80:83]
	ds_read_b128 v[224:227], v109 offset:16768
	s_waitcnt lgkmcnt(7)
	v_mfma_f32_16x16x32_bf16 v[156:159], v[228:231], v[4:7], v[0:3]
	v_mfma_f32_16x16x32_bf16 v[152:155], v[228:231], v[16:19], v[0:3]
	ds_read_b128 v[228:231], v109 offset:20096
	s_waitcnt lgkmcnt(5)
	v_mfma_f32_16x16x32_bf16 v[156:159], v[240:243], v[8:11], v[156:159]
	v_mfma_f32_16x16x32_bf16 v[152:155], v[240:243], v[20:23], v[152:155]
	ds_read_b128 v[240:243], v109 offset:23424
	v_mfma_f32_16x16x32_bf16 v[164:167], v[232:235], v[4:7], v[0:3]
	v_mfma_f32_16x16x32_bf16 v[160:163], v[232:235], v[16:19], v[0:3]
	s_waitcnt lgkmcnt(5)
	v_mfma_f32_16x16x32_bf16 v[164:167], v[244:247], v[8:11], v[164:167]
	v_mfma_f32_16x16x32_bf16 v[160:163], v[244:247], v[20:23], v[160:163]
	v_mfma_f32_16x16x32_bf16 v[190:193], v[236:239], v[4:7], v[0:3]
	v_mfma_f32_16x16x32_bf16 v[168:171], v[236:239], v[16:19], v[0:3]
	s_waitcnt lgkmcnt(4)
	v_mfma_f32_16x16x32_bf16 v[190:193], v[248:251], v[8:11], v[190:193]
	v_mfma_f32_16x16x32_bf16 v[168:171], v[248:251], v[20:23], v[168:171]
	s_waitcnt lgkmcnt(3)
	v_mfma_f32_16x16x32_bf16 v[148:151], v[220:223], v[12:15], v[148:151]
	v_mfma_f32_16x16x32_bf16 v[194:197], v[220:223], v[24:27], v[80:83]
	s_waitcnt lgkmcnt(2)
	v_mfma_f32_16x16x32_bf16 v[198:201], v[224:227], v[12:15], v[156:159]
	v_mfma_f32_16x16x32_bf16 v[202:205], v[224:227], v[24:27], v[152:155]
	s_waitcnt lgkmcnt(1)
	v_mfma_f32_16x16x32_bf16 v[206:209], v[228:231], v[12:15], v[164:167]
	v_mfma_f32_16x16x32_bf16 v[210:213], v[228:231], v[24:27], v[160:163]
	s_waitcnt lgkmcnt(0)
	v_mfma_f32_16x16x32_bf16 v[190:193], v[240:243], v[12:15], v[190:193]
	v_mfma_f32_16x16x32_bf16 v[214:217], v[240:243], v[24:27], v[168:171]
	s_nop 1
	s_setprio 0
	v_mul_f32_e32 v80, 0x3e16c740, v148
	v_mul_f32_e32 v81, 0x3e16c740, v149
	v_max3_f32 v80, v80, s68, v81
	v_mul_f32_e32 v81, 0x3e16c740, v150
	v_mul_f32_e32 v82, 0x3e16c740, v151
	v_max3_f32 v80, v80, v81, v82
	v_mul_f32_e32 v81, 0x3e16c740, v198
	v_mul_f32_e32 v82, 0x3e16c740, v199
	v_max3_f32 v80, v80, v81, v82
	v_mul_f32_e32 v81, 0x3e16c740, v200
	v_mul_f32_e32 v82, 0x3e16c740, v201
	v_max3_f32 v80, v80, v81, v82
	v_mul_f32_e32 v81, 0x3e16c740, v206
	v_mul_f32_e32 v82, 0x3e16c740, v207
	v_max3_f32 v80, v80, v81, v82
	v_mul_f32_e32 v81, 0x3e16c740, v208
	v_mul_f32_e32 v82, 0x3e16c740, v209
	v_max3_f32 v80, v80, v81, v82
	v_mul_f32_e32 v81, 0x3e16c740, v190
	v_mul_f32_e32 v82, 0x3e16c740, v191
	v_max3_f32 v80, v80, v81, v82
	v_mul_f32_e32 v81, 0x3e16c740, v192
	v_mul_f32_e32 v82, 0x3e16c740, v193
	v_max3_f32 v80, v80, v81, v82
	v_mov_b32_e32 v81, v80
	s_nop 1
	v_permlane16_swap_b32_e32 v80, v81
	v_max_f32_e32 v81, v81, v81
	v_max_f32_e32 v80, v80, v80
	v_max_f32_e32 v80, v80, v81
	v_mov_b32_e32 v81, v80
	s_nop 1
	v_permlane32_swap_b32_e32 v80, v81
	v_max3_f32 v81, v144, v80, v81
	v_fma_f32 v82, v148, s38, -v81
	v_exp_f32_e32 v171, v82
	v_fma_f32 v82, v149, s38, -v81
	v_exp_f32_e32 v169, v82
	v_fma_f32 v82, v150, s38, -v81
	v_exp_f32_e32 v167, v82
	v_fma_f32 v82, v151, s38, -v81
	v_exp_f32_e32 v165, v82
	v_fma_f32 v82, v198, s38, -v81
	v_exp_f32_e32 v163, v82
	v_fma_f32 v82, v199, s38, -v81
	v_exp_f32_e32 v161, v82
	v_fma_f32 v82, v200, s38, -v81
	v_exp_f32_e32 v159, v82
	v_fma_f32 v82, v201, s38, -v81
	v_exp_f32_e32 v157, v82
	v_fma_f32 v82, v206, s38, -v81
	v_exp_f32_e32 v155, v82
	v_fma_f32 v82, v207, s38, -v81
	v_exp_f32_e32 v153, v82
	v_fma_f32 v82, v208, s38, -v81
	v_exp_f32_e32 v151, v82
	v_fma_f32 v82, v209, s38, -v81
	v_exp_f32_e32 v147, v82
	v_fma_f32 v82, v190, s38, -v81
	v_exp_f32_e32 v87, v82
	v_fma_f32 v82, v191, s38, -v81
	v_exp_f32_e32 v83, v82
	v_fma_f32 v82, v192, s38, -v81
	v_exp_f32_e32 v149, v82
	v_fma_f32 v82, v193, s38, -v81
	v_exp_f32_e32 v145, v82
	v_mul_f32_e32 v82, 0x3e16c740, v194
	v_mul_f32_e32 v86, 0x3e16c740, v195
	v_max3_f32 v82, v82, s68, v86
	v_mul_f32_e32 v86, 0x3e16c740, v196
	v_mul_f32_e32 v109, 0x3e16c740, v197
	v_max3_f32 v82, v82, v86, v109
	v_mul_f32_e32 v86, 0x3e16c740, v202
	v_mul_f32_e32 v109, 0x3e16c740, v203
	v_max3_f32 v82, v82, v86, v109
	v_mul_f32_e32 v86, 0x3e16c740, v204
	v_mul_f32_e32 v109, 0x3e16c740, v205
	v_max3_f32 v82, v82, v86, v109
	v_mul_f32_e32 v86, 0x3e16c740, v210
	v_mul_f32_e32 v109, 0x3e16c740, v211
	v_max3_f32 v82, v82, v86, v109
	v_mul_f32_e32 v86, 0x3e16c740, v212
	v_mul_f32_e32 v109, 0x3e16c740, v213
	v_max3_f32 v82, v82, v86, v109
	v_mul_f32_e32 v86, 0x3e16c740, v214
	v_mul_f32_e32 v109, 0x3e16c740, v215
	v_max3_f32 v82, v82, v86, v109
	v_mul_f32_e32 v86, 0x3e16c740, v216
	v_mul_f32_e32 v109, 0x3e16c740, v217
	v_max3_f32 v82, v82, v86, v109
	v_mov_b32_e32 v86, v82
	s_nop 1
	v_permlane16_swap_b32_e32 v82, v86
	v_max_f32_e32 v86, v86, v86
	v_max_f32_e32 v82, v82, v82
	v_max_f32_e32 v82, v82, v86
	v_mov_b32_e32 v86, v82
	s_nop 1
	v_permlane32_swap_b32_e32 v82, v86
	v_max3_f32 v189, v146, v82, v86
	v_fma_f32 v82, v194, s38, -v189
	v_exp_f32_e32 v170, v82
	v_fma_f32 v82, v195, s38, -v189
	v_exp_f32_e32 v168, v82
	v_fma_f32 v82, v196, s38, -v189
	v_exp_f32_e32 v166, v82
	v_fma_f32 v82, v197, s38, -v189
	v_exp_f32_e32 v164, v82
	v_fma_f32 v82, v202, s38, -v189
	v_exp_f32_e32 v162, v82
	v_fma_f32 v82, v203, s38, -v189
	v_exp_f32_e32 v160, v82
	v_fma_f32 v82, v204, s38, -v189
	v_exp_f32_e32 v158, v82
	v_fma_f32 v82, v205, s38, -v189
	v_exp_f32_e32 v156, v82
	v_fma_f32 v82, v210, s38, -v189
	v_exp_f32_e32 v154, v82
	v_fma_f32 v82, v211, s38, -v189
	v_exp_f32_e32 v152, v82
	v_fma_f32 v82, v212, s38, -v189
	v_exp_f32_e32 v150, v82
	v_fma_f32 v82, v213, s38, -v189
	v_sub_f32_e32 v80, v144, v81
	v_sub_f32_e32 v109, v146, v189
	v_exp_f32_e32 v146, v82
	v_fma_f32 v82, v214, s38, -v189
	v_exp_f32_e32 v80, v80
	v_exp_f32_e32 v86, v82
	v_fma_f32 v82, v215, s38, -v189
	v_fma_f32 v144, v216, s38, -v189
	v_exp_f32_e32 v172, v109
	v_fma_f32 v109, v217, s38, -v189
	v_exp_f32_e32 v82, v82
	v_exp_f32_e32 v148, v144
	v_exp_f32_e32 v144, v109
	v_pk_mul_f32 v[70:71], v[70:71], v[80:81] op_sel_hi:[1,0]
	v_pk_mul_f32 v[68:69], v[68:69], v[80:81] op_sel_hi:[1,0]
	v_pk_mul_f32 v[66:67], v[66:67], v[80:81] op_sel_hi:[1,0]
	v_pk_mul_f32 v[64:65], v[64:65], v[80:81] op_sel_hi:[1,0]
	v_pk_mul_f32 v[74:75], v[74:75], v[80:81] op_sel_hi:[1,0]
	v_pk_mul_f32 v[72:73], v[72:73], v[80:81] op_sel_hi:[1,0]
	v_pk_mul_f32 v[192:193], v[78:79], v[80:81] op_sel_hi:[1,0]
	v_pk_mul_f32 v[190:191], v[76:77], v[80:81] op_sel_hi:[1,0]
	v_cvt_pk_bf16_f32 v76, v155, v153
	v_cvt_pk_bf16_f32 v77, v151, v147
	v_cvt_pk_bf16_f32 v78, v87, v83
	v_cvt_pk_bf16_f32 v79, v149, v145
	v_pk_mul_f32 v[54:55], v[54:55], v[172:173] op_sel_hi:[1,0]
	v_pk_mul_f32 v[52:53], v[52:53], v[172:173] op_sel_hi:[1,0]
	v_pk_mul_f32 v[50:51], v[50:51], v[172:173] op_sel_hi:[1,0]
	v_pk_mul_f32 v[48:49], v[48:49], v[172:173] op_sel_hi:[1,0]
	v_pk_mul_f32 v[58:59], v[58:59], v[172:173] op_sel_hi:[1,0]
	v_pk_mul_f32 v[56:57], v[56:57], v[172:173] op_sel_hi:[1,0]
	v_pk_mul_f32 v[62:63], v[62:63], v[172:173] op_sel_hi:[1,0]
	v_pk_mul_f32 v[60:61], v[60:61], v[172:173] op_sel_hi:[1,0]
	v_cvt_pk_bf16_f32 v198, v171, v169
	v_cvt_pk_bf16_f32 v199, v167, v165
	v_cvt_pk_bf16_f32 v200, v163, v161
	v_cvt_pk_bf16_f32 v201, v159, v157
	v_cvt_pk_bf16_f32 v194, v170, v168
	v_cvt_pk_bf16_f32 v195, v166, v164
	v_cvt_pk_bf16_f32 v196, v162, v160
	v_cvt_pk_bf16_f32 v197, v158, v156
	v_cvt_pk_bf16_f32 v202, v154, v152
	v_cvt_pk_bf16_f32 v203, v150, v146
	v_cvt_pk_bf16_f32 v204, v86, v82
	v_cvt_pk_bf16_f32 v205, v148, v144
	s_setprio 1
	ds_read_b64_tr_b16 v[222:223], v85 offset:39424
	ds_read_b64_tr_b16 v[220:221], v85 offset:36864
	ds_read_b64_tr_b16 v[224:225], v85 offset:36896
	ds_read_b64_tr_b16 v[226:227], v85 offset:39456
	ds_read_b64_tr_b16 v[228:229], v85 offset:41984
	ds_read_b64_tr_b16 v[230:231], v85 offset:44544
	ds_read_b64_tr_b16 v[232:233], v85 offset:42016
	ds_read_b64_tr_b16 v[234:235], v85 offset:44576
	ds_read_b64_tr_b16 v[236:237], v85 offset:36928
	ds_read_b64_tr_b16 v[238:239], v85 offset:39488
	ds_read_b64_tr_b16 v[240:241], v85 offset:42048
	ds_read_b64_tr_b16 v[242:243], v85 offset:44608
	ds_read_b64_tr_b16 v[244:245], v85 offset:36960
	ds_read_b64_tr_b16 v[246:247], v85 offset:39520
	ds_read_b64_tr_b16 v[248:249], v85 offset:42080
	ds_read_b64_tr_b16 v[250:251], v85 offset:44640
	s_waitcnt lgkmcnt(14)
	v_mfma_f32_16x16x32_bf16 v[68:71], v[220:223], v[198:201], v[68:71]
	v_mfma_f32_16x16x32_bf16 v[52:55], v[220:223], v[194:197], v[52:55]
	s_waitcnt lgkmcnt(10)
	v_mfma_f32_16x16x32_bf16 v[68:71], v[228:231], v[76:79], v[68:71]
	v_mfma_f32_16x16x32_bf16 v[52:55], v[228:231], v[202:205], v[52:55]
	v_mfma_f32_16x16x32_bf16 v[64:67], v[224:227], v[198:201], v[64:67]
	v_mfma_f32_16x16x32_bf16 v[48:51], v[224:227], v[194:197], v[48:51]
	s_waitcnt lgkmcnt(8)
	v_mfma_f32_16x16x32_bf16 v[64:67], v[232:235], v[76:79], v[64:67]
	v_mfma_f32_16x16x32_bf16 v[48:51], v[232:235], v[202:205], v[48:51]
	s_waitcnt lgkmcnt(6)
	v_mfma_f32_16x16x32_bf16 v[72:75], v[236:239], v[198:201], v[72:75]
	v_mfma_f32_16x16x32_bf16 v[56:59], v[236:239], v[194:197], v[56:59]
	s_waitcnt lgkmcnt(4)
	v_mfma_f32_16x16x32_bf16 v[72:75], v[240:243], v[76:79], v[72:75]
	v_mfma_f32_16x16x32_bf16 v[56:59], v[240:243], v[202:205], v[56:59]
	s_waitcnt lgkmcnt(2)
	v_mfma_f32_16x16x32_bf16 v[60:63], v[244:247], v[194:197], v[60:63]
	v_mfma_f32_16x16x32_bf16 v[190:193], v[244:247], v[198:201], v[190:193]
	s_waitcnt lgkmcnt(0)
	v_mfma_f32_16x16x32_bf16 v[76:79], v[248:251], v[76:79], v[190:193]
	v_mfma_f32_16x16x32_bf16 v[60:63], v[248:251], v[202:205], v[60:63]
	s_nop 3
	s_setprio 0
	s_add_i32 s22, s10, 1
	s_cmp_ge_u32 s22, s19
	s_cbranch_scc1 .LBB0_2970
	s_bitcmp1_b32 s22, 0
	s_cselect_b32 s11, 0xb800, 0
	v_add3_u32 v85, s11, v95, v96
	s_waitcnt vmcnt(0)
	ds_write_b128 v85, v[28:31]
	v_add3_u32 v85, s11, v99, v96
	ds_write_b128 v85, v[36:39]
	v_add3_u32 v85, s11, v184, v96
	ds_write_b128 v85, v[32:35] offset:26624
	v_add3_u32 v85, s11, v185, v96
	ds_write_b128 v85, v[40:43] offset:26624
	v_add3_u32 v85, s11, v111, v98
	ds_write_b128 v85, v[44:47] offset:128

.LBB0_3020:
	s_and_b64 s[18:19], s[6:7], exec
	s_mov_b32 s18, 0xd7f2000
	s_cselect_b32 s18, s18, 0xddf2000
	s_add_u32 s18, s8, s18
	s_addc_u32 s19, s9, 0
	v_lshl_add_u64 v[136:137], v[20:21], 1, s[18:19]
	s_mov_b64 s[18:19], 0x3000
	v_lshl_add_u64 v[136:137], v[136:137], 0, s[18:19]
	global_load_dwordx2 v[140:141], v[136:137], off offset:-4096
	global_load_dwordx2 v[142:143], v[136:137], off
	v_lshl_add_u64 v[138:139], v[136:137], 0, s[52:53]
	global_load_dwordx2 v[144:145], v[138:139], off offset:-4096
	global_load_dwordx2 v[146:147], v[138:139], off
	s_andn2_b64 vcc, exec, s[10:11]
	v_mov_b32_e32 v7, v0
	v_mov_b32_e32 v6, v0
	v_mov_b32_e32 v5, v0
	v_mov_b32_e32 v4, v0
	v_mov_b32_e32 v11, v0
	v_mov_b32_e32 v10, v0
	v_mov_b32_e32 v9, v0
	v_mov_b32_e32 v8, v0
	v_mov_b32_e32 v15, v0
	v_mov_b32_e32 v14, v0
	v_mov_b32_e32 v13, v0
	v_mov_b32_e32 v12, v0
	v_mov_b32_e32 v19, v0
	v_mov_b32_e32 v18, v0
	v_mov_b32_e32 v17, v0
	v_mov_b32_e32 v16, v0
	s_cbranch_vccnz .LBB0_3023
	v_or_b32_e32 v4, s12, v36
	s_and_b64 s[12:13], s[6:7], exec
	s_movk_i32 s12, 0x5380
	s_cselect_b32 s12, s12, 0xa380
	s_movk_i32 s13, 0x1060
	v_mad_u32_u24 v30, v4, s13, v38
	v_add_u32_e32 v31, s12, v39
	s_mov_b32 s12, s16
	v_mov_b32_e32 v16, v0
	v_mov_b32_e32 v17, v0
	v_mov_b32_e32 v18, v0
	v_mov_b32_e32 v19, v0
	v_mov_b32_e32 v12, v0
	v_mov_b32_e32 v13, v0
	v_mov_b32_e32 v14, v0
	v_mov_b32_e32 v15, v0
	v_mov_b32_e32 v8, v0
	v_mov_b32_e32 v9, v0
	v_mov_b32_e32 v10, v0
	v_mov_b32_e32 v11, v0
	v_mov_b32_e32 v4, v0
	v_mov_b32_e32 v5, v0
	v_mov_b32_e32 v6, v0
	v_mov_b32_e32 v7, v0

.Lhy_lat1_done:
.LBB0_3023:
	s_xor_b64 s[12:13], s[6:7], -1
	s_and_b64 s[18:19], s[6:7], exec
	s_cselect_b32 s18, s2, 0xddf2000
	s_add_u32 s18, s8, s18
	s_addc_u32 s19, s9, 0
	v_cndmask_b32_e64 v30, v35, v34, s[6:7]
	s_and_b64 s[6:7], s[6:7], exec
	s_mov_b32 s6, 0x9380
	s_cselect_b32 s6, 0x4380, s6
	v_lshl_add_u64 v[32:33], v[20:21], 1, s[18:19]
	v_lshl_add_u32 v31, v20, 1, s6
	s_movk_i32 s6, 0x2000
	v_add_co_u32_e32 v42, vcc, s6, v32
	ds_read_b64 v[40:41], v31
	s_nop 0
	v_addc_co_u32_e32 v43, vcc, 0, v33, vcc
	v_mov_b32_e32 v49, v18
	s_waitcnt lgkmcnt(0)
	v_lshlrev_b32_e32 v47, 16, v41
	v_lshlrev_b32_e32 v46, 16, v40
	v_and_b32_e32 v41, 0xffff0000, v41
	v_and_b32_e32 v40, 0xffff0000, v40
	v_mov_b32_e32 v18, v17
	v_mov_b32_e32 v48, v16
	v_pk_fma_f32 v[16:17], v[30:31], v[40:41], v[18:19] op_sel_hi:[0,1,1]
	v_pk_fma_f32 v[46:47], v[30:31], v[46:47], v[48:49] op_sel_hi:[0,1,1]
	s_mov_b64 s[6:7], -1
	s_and_b64 vcc, exec, s[12:13]
	s_waitcnt vmcnt(0)
	v_lshlrev_b32_e32 v45, 16, v141
	v_lshlrev_b32_e32 v44, 16, v140
	v_and_b32_e32 v43, 0xffff0000, v141
	v_and_b32_e32 v42, 0xffff0000, v140
	v_pk_mul_f32 v[16:17], v[16:17], v[42:43]
	v_pk_mul_f32 v[44:45], v[46:47], v[44:45]
	v_and_b32_sdwa v31, v17, v176 dst_sel:DWORD dst_unused:UNUSED_PAD src0_sel:WORD_1 src1_sel:DWORD
	v_and_b32_sdwa v40, v16, v176 dst_sel:DWORD dst_unused:UNUSED_PAD src0_sel:WORD_1 src1_sel:DWORD
	v_and_b32_sdwa v18, v45, v176 dst_sel:DWORD dst_unused:UNUSED_PAD src0_sel:WORD_1 src1_sel:DWORD
	v_and_b32_sdwa v19, v44, v176 dst_sel:DWORD dst_unused:UNUSED_PAD src0_sel:WORD_1 src1_sel:DWORD
	v_add3_u32 v17, v17, v31, s93
	v_add3_u32 v16, v16, v40, s93
	v_add3_u32 v19, v44, v19, s93
	v_add3_u32 v18, v45, v18, s93
	v_and_b32_e32 v17, 0xffff0000, v17
	v_and_b32_e32 v16, 0xffff0000, v16
	v_or_b32_sdwa v17, v17, v18 dst_sel:DWORD dst_unused:UNUSED_PAD src0_sel:DWORD src1_sel:WORD_1
	v_or_b32_sdwa v16, v16, v19 dst_sel:DWORD dst_unused:UNUSED_PAD src0_sel:DWORD src1_sel:WORD_1
	s_cbranch_vccz .LBB0_3025
	flat_store_dwordx2 v[22:23], v[16:17]
	s_mov_b64 s[6:7], 0

.LBB0_3027:
	v_lshl_add_u64 v[16:17], v[32:33], 0, s[52:53]
	v_add_co_u32_e32 v18, vcc, 0x1000, v16
	v_lshl_add_u32 v40, v20, 1, s6
	s_nop 0
	v_addc_co_u32_e32 v19, vcc, 0, v17, vcc
	ds_read_b64 v[40:41], v40 offset:512
	v_mov_b32_e32 v32, v12
	v_cndmask_b32_e64 v12, 0, 1, s[12:13]
	v_mov_b32_e32 v31, v30
	v_mov_b32_e32 v33, v14
	v_mov_b32_e32 v14, v13
	v_cmp_ne_u32_e64 s[6:7], 1, v12
	s_waitcnt lgkmcnt(0)
	v_lshlrev_b32_e32 v13, 16, v41
	v_lshlrev_b32_e32 v12, 16, v40
	v_and_b32_e32 v41, 0xffff0000, v41
	v_and_b32_e32 v40, 0xffff0000, v40
	v_pk_fma_f32 v[12:13], v[30:31], v[12:13], v[32:33]
	v_pk_fma_f32 v[14:15], v[30:31], v[40:41], v[14:15]
	s_andn2_b64 vcc, exec, s[12:13]
	s_mov_b64 s[12:13], -1
	v_lshlrev_b32_e32 v33, 16, v143
	v_lshlrev_b32_e32 v32, 16, v142
	v_and_b32_e32 v19, 0xffff0000, v143
	v_and_b32_e32 v18, 0xffff0000, v142
	v_pk_mul_f32 v[14:15], v[14:15], v[18:19]
	v_pk_mul_f32 v[12:13], v[12:13], v[32:33]
	v_and_b32_sdwa v32, v15, v176 dst_sel:DWORD dst_unused:UNUSED_PAD src0_sel:WORD_1 src1_sel:DWORD
	v_and_b32_sdwa v33, v14, v176 dst_sel:DWORD dst_unused:UNUSED_PAD src0_sel:WORD_1 src1_sel:DWORD
	v_and_b32_sdwa v18, v13, v176 dst_sel:DWORD dst_unused:UNUSED_PAD src0_sel:WORD_1 src1_sel:DWORD
	v_and_b32_sdwa v19, v12, v176 dst_sel:DWORD dst_unused:UNUSED_PAD src0_sel:WORD_1 src1_sel:DWORD
	v_add3_u32 v15, v15, v32, s93
	v_add3_u32 v14, v14, v33, s93
	v_add3_u32 v12, v12, v19, s93
	v_add3_u32 v13, v13, v18, s93
	v_and_b32_e32 v15, 0xffff0000, v15
	v_and_b32_e32 v14, 0xffff0000, v14
	v_or_b32_sdwa v13, v15, v13 dst_sel:DWORD dst_unused:UNUSED_PAD src0_sel:DWORD src1_sel:WORD_1
	v_or_b32_sdwa v12, v14, v12 dst_sel:DWORD dst_unused:UNUSED_PAD src0_sel:DWORD src1_sel:WORD_1
	s_cbranch_vccnz .LBB0_3029
	s_mov_b64 s[12:13], 0
	flat_store_dwordx2 v[24:25], v[12:13]

.LBB0_3031:
	v_add_co_u32_e32 v12, vcc, 0x2000, v16
	v_lshl_add_u32 v14, v20, 1, s12
	s_nop 0
	v_addc_co_u32_e32 v13, vcc, 0, v17, vcc
	ds_read_b64 v[14:15], v14 offset:512
	v_mov_b32_e32 v18, v8
	v_mov_b32_e32 v19, v10
	v_mov_b32_e32 v10, v9
	s_and_b64 vcc, exec, s[6:7]
	s_waitcnt lgkmcnt(0)
	v_lshlrev_b32_e32 v9, 16, v15
	v_lshlrev_b32_e32 v8, 16, v14
	v_and_b32_e32 v15, 0xffff0000, v15
	v_and_b32_e32 v14, 0xffff0000, v14
	v_pk_fma_f32 v[10:11], v[30:31], v[14:15], v[10:11]
	v_pk_fma_f32 v[8:9], v[30:31], v[8:9], v[18:19]
	s_mov_b64 s[12:13], -1
	v_lshlrev_b32_e32 v15, 16, v145
	v_lshlrev_b32_e32 v14, 16, v144
	v_and_b32_e32 v13, 0xffff0000, v145
	v_and_b32_e32 v12, 0xffff0000, v144
	v_pk_mul_f32 v[10:11], v[10:11], v[12:13]
	v_pk_mul_f32 v[8:9], v[8:9], v[14:15]
	v_and_b32_sdwa v14, v11, v176 dst_sel:DWORD dst_unused:UNUSED_PAD src0_sel:WORD_1 src1_sel:DWORD
	v_and_b32_sdwa v15, v10, v176 dst_sel:DWORD dst_unused:UNUSED_PAD src0_sel:WORD_1 src1_sel:DWORD
	v_and_b32_sdwa v12, v9, v176 dst_sel:DWORD dst_unused:UNUSED_PAD src0_sel:WORD_1 src1_sel:DWORD
	v_and_b32_sdwa v13, v8, v176 dst_sel:DWORD dst_unused:UNUSED_PAD src0_sel:WORD_1 src1_sel:DWORD
	v_add3_u32 v11, v11, v14, s93
	v_add3_u32 v10, v10, v15, s93
	v_add3_u32 v8, v8, v13, s93
	v_add3_u32 v9, v9, v12, s93
	v_and_b32_e32 v11, 0xffff0000, v11
	v_and_b32_e32 v10, 0xffff0000, v10
	v_or_b32_sdwa v9, v11, v9 dst_sel:DWORD dst_unused:UNUSED_PAD src0_sel:DWORD src1_sel:WORD_1
	v_or_b32_sdwa v8, v10, v8 dst_sel:DWORD dst_unused:UNUSED_PAD src0_sel:DWORD src1_sel:WORD_1
	s_cbranch_vccnz .LBB0_3033
	s_mov_b64 s[12:13], 0
	flat_store_dwordx2 v[26:27], v[8:9]

.LBB0_3035:
	v_add_co_u32_e32 v8, vcc, 0x3000, v16
	v_lshl_add_u32 v10, v20, 1, s12
	s_nop 0
	v_addc_co_u32_e32 v9, vcc, 0, v17, vcc
	ds_read_b64 v[10:11], v10 offset:512
	v_mov_b32_e32 v12, v4
	v_mov_b32_e32 v13, v6
	v_mov_b32_e32 v6, v5
	s_and_b64 vcc, exec, s[6:7]
	s_waitcnt lgkmcnt(0)
	v_lshlrev_b32_e32 v5, 16, v11
	v_lshlrev_b32_e32 v4, 16, v10
	v_and_b32_e32 v11, 0xffff0000, v11
	v_and_b32_e32 v10, 0xffff0000, v10
	v_pk_fma_f32 v[6:7], v[30:31], v[10:11], v[6:7]
	v_pk_fma_f32 v[4:5], v[30:31], v[4:5], v[12:13]
	s_mov_b64 s[12:13], -1
	v_lshlrev_b32_e32 v11, 16, v147
	v_lshlrev_b32_e32 v10, 16, v146
	v_and_b32_e32 v9, 0xffff0000, v147
	v_and_b32_e32 v8, 0xffff0000, v146
	v_pk_mul_f32 v[6:7], v[6:7], v[8:9]
	v_pk_mul_f32 v[4:5], v[4:5], v[10:11]
	v_and_b32_sdwa v10, v7, v176 dst_sel:DWORD dst_unused:UNUSED_PAD src0_sel:WORD_1 src1_sel:DWORD
	v_and_b32_sdwa v11, v6, v176 dst_sel:DWORD dst_unused:UNUSED_PAD src0_sel:WORD_1 src1_sel:DWORD
	v_and_b32_sdwa v8, v5, v176 dst_sel:DWORD dst_unused:UNUSED_PAD src0_sel:WORD_1 src1_sel:DWORD
	v_and_b32_sdwa v9, v4, v176 dst_sel:DWORD dst_unused:UNUSED_PAD src0_sel:WORD_1 src1_sel:DWORD
	v_add3_u32 v7, v7, v10, s93
	v_add3_u32 v6, v6, v11, s93
	v_add3_u32 v4, v4, v9, s93
	v_add3_u32 v5, v5, v8, s93
	v_and_b32_e32 v7, 0xffff0000, v7
	v_and_b32_e32 v6, 0xffff0000, v6
	v_or_b32_sdwa v5, v7, v5 dst_sel:DWORD dst_unused:UNUSED_PAD src0_sel:DWORD src1_sel:WORD_1
	v_or_b32_sdwa v4, v6, v4 dst_sel:DWORD dst_unused:UNUSED_PAD src0_sel:DWORD src1_sel:WORD_1
	s_cbranch_vccnz .LBB0_3037
	s_mov_b64 s[12:13], 0
	flat_store_dwordx2 v[28:29], v[4:5]

.LBB0_3058:
	s_bitcmp1_b32 s82, 0
	s_cselect_b32 s83, 0x9800, 0
	s_cmp_lt_i32 s82, s76
	s_cselect_b64 s[6:7], -1, 0
	s_and_b64 s[74:75], s[70:71], s[6:7]
	s_setprio 1
	v_or_b32_e32 v68, s83, v94
	v_add_u32_e32 v88, v68, v163
	ds_read_b128 v[204:207], v88 offset:2304
	ds_read_b128 v[208:211], v88
	ds_read_b128 v[212:215], v88 offset:4608
	ds_read_b128 v[216:219], v88 offset:6912
	ds_read_b128 v[220:223], v88 offset:64
	ds_read_b128 v[224:227], v88 offset:2368
	ds_read_b128 v[228:231], v88 offset:4672
	ds_read_b128 v[232:235], v88 offset:6976
	s_waitcnt lgkmcnt(7)
	v_mfma_f32_16x16x32_bf16 v[82:85], v[204:207], v[4:7], v[0:3]
	v_mfma_f32_16x16x32_bf16 v[108:111], v[204:207], v[12:15], v[0:3]
	s_waitcnt lgkmcnt(5)
	v_mfma_f32_16x16x32_bf16 v[112:115], v[212:215], v[4:7], v[0:3]
	v_mfma_f32_16x16x32_bf16 v[116:119], v[212:215], v[12:15], v[0:3]
	s_waitcnt lgkmcnt(4)
	v_mfma_f32_16x16x32_bf16 v[120:123], v[216:219], v[4:7], v[0:3]
	v_mfma_f32_16x16x32_bf16 v[124:127], v[216:219], v[12:15], v[0:3]
	v_mfma_f32_16x16x32_bf16 v[74:77], v[208:211], v[4:7], v[0:3]
	v_mfma_f32_16x16x32_bf16 v[68:71], v[208:211], v[12:15], v[0:3]
	s_waitcnt lgkmcnt(3)
	v_mfma_f32_16x16x32_bf16 v[128:131], v[220:223], v[8:11], v[74:77]
	v_mfma_f32_16x16x32_bf16 v[76:79], v[220:223], v[16:19], v[68:71]
	s_waitcnt lgkmcnt(2)
	v_mfma_f32_16x16x32_bf16 v[132:135], v[224:227], v[8:11], v[82:85]
	v_mfma_f32_16x16x32_bf16 v[80:83], v[224:227], v[16:19], v[108:111]
	s_waitcnt lgkmcnt(1)
	v_mfma_f32_16x16x32_bf16 v[108:111], v[228:231], v[8:11], v[112:115]
	v_mfma_f32_16x16x32_bf16 v[84:87], v[228:231], v[16:19], v[116:119]
	s_waitcnt lgkmcnt(0)
	v_mfma_f32_16x16x32_bf16 v[112:115], v[232:235], v[8:11], v[120:123]
	v_mfma_f32_16x16x32_bf16 v[142:145], v[232:235], v[16:19], v[124:127]
	s_nop 1
	s_setprio 0
	v_add_u32_e32 v69, 0x73, v166
	v_cmp_gt_u32_e32 vcc, s39, v69
	v_add_u32_e32 v70, 0x72, v166
	s_and_b64 s[12:13], s[74:75], vcc
	v_cmp_gt_u32_e32 vcc, s39, v70
	v_add_u32_e32 v72, 0x71, v166
	s_and_b64 s[14:15], s[74:75], vcc
	v_cmp_gt_u32_e32 vcc, s39, v72
	v_add_u32_e32 v74, 0x70, v166
	s_and_b64 s[16:17], s[74:75], vcc
	v_cmp_gt_u32_e32 vcc, s39, v74
	v_add_u32_e32 v75, 0x63, v166
	s_and_b64 s[18:19], s[74:75], vcc
	v_cmp_gt_u32_e32 vcc, s39, v75
	v_add_u32_e32 v106, 0x62, v166
	s_and_b64 s[20:21], s[74:75], vcc
	v_cmp_gt_u32_e32 vcc, s39, v106
	v_add_u32_e32 v116, 0x61, v166
	s_and_b64 s[22:23], s[74:75], vcc
	v_cmp_gt_u32_e32 vcc, s39, v116
	v_add_u32_e32 v117, 0x60, v166
	s_and_b64 s[24:25], s[74:75], vcc
	v_cmp_gt_u32_e32 vcc, s39, v117
	v_add_u32_e32 v117, 0x53, v166
	s_and_b64 s[26:27], s[74:75], vcc
	v_cmp_gt_u32_e32 vcc, s39, v117
	v_add_u32_e32 v117, 0x52, v166
	v_mul_f32_e32 v68, 0x3e38aa3b, v128
	v_mul_f32_e32 v69, 0x3e38aa3b, v129
	s_and_b64 s[28:29], s[74:75], vcc
	v_cmp_gt_u32_e32 vcc, s39, v117
	v_add_u32_e32 v117, 0x51, v166
	v_cndmask_b32_e64 v68, v68, v181, s[12:13]
	v_cndmask_b32_e64 v69, v69, v181, s[14:15]
	v_mul_f32_e32 v71, 0x3e38aa3b, v130
	v_mul_f32_e32 v72, 0x3e38aa3b, v131
	s_and_b64 s[30:31], s[74:75], vcc
	v_cmp_gt_u32_e32 vcc, s39, v117
	v_add_u32_e32 v117, 0x50, v166
	v_max3_f32 v70, v68, s68, v69
	v_cndmask_b32_e64 v71, v71, v181, s[16:17]
	v_cndmask_b32_e64 v72, v72, v181, s[18:19]
	v_mul_f32_e32 v74, 0x3e38aa3b, v132
	v_mul_f32_e32 v75, 0x3e38aa3b, v133
	s_and_b64 s[34:35], s[74:75], vcc
	v_cmp_gt_u32_e32 vcc, s39, v117
	v_add_u32_e32 v117, 0x43, v166
	v_max3_f32 v70, v70, v71, v72
	v_cndmask_b32_e64 v74, v74, v181, s[20:21]
	v_cndmask_b32_e64 v75, v75, v181, s[22:23]
	v_mul_f32_e32 v106, 0x3e38aa3b, v134
	v_mul_f32_e32 v116, 0x3e38aa3b, v135
	s_and_b64 s[36:37], s[74:75], vcc
	v_cmp_gt_u32_e32 vcc, s39, v117
	v_add_u32_e32 v117, 0x42, v166
	v_max3_f32 v70, v70, v74, v75
	v_cndmask_b32_e64 v106, v106, v181, s[24:25]
	v_cndmask_b32_e64 v116, v116, v181, s[26:27]
	v_mul_f32_e32 v108, 0x3e38aa3b, v108
	v_mul_f32_e32 v109, 0x3e38aa3b, v109
	v_cmp_gt_u32_e64 s[6:7], s39, v117
	v_add_u32_e32 v117, 0x41, v166
	v_max3_f32 v70, v70, v106, v116
	v_cndmask_b32_e64 v108, v108, v181, s[28:29]
	v_cndmask_b32_e64 v109, v109, v181, s[30:31]
	v_mul_f32_e32 v110, 0x3e38aa3b, v110
	v_mul_f32_e32 v111, 0x3e38aa3b, v111
	v_cmp_gt_u32_e64 s[8:9], s39, v117
	v_add_u32_e32 v117, 64, v166
	v_max3_f32 v70, v70, v108, v109
	v_cndmask_b32_e64 v110, v110, v181, s[34:35]
	v_cndmask_b32_e64 v111, v111, v181, s[36:37]
	v_mul_f32_e32 v112, 0x3e38aa3b, v112
	s_and_b64 vcc, s[74:75], vcc
	v_mul_f32_e32 v113, 0x3e38aa3b, v113
	s_and_b64 s[6:7], s[74:75], s[6:7]
	v_cmp_gt_u32_e64 s[10:11], s39, v117
	v_max3_f32 v70, v70, v110, v111
	v_cndmask_b32_e32 v112, v112, v181, vcc
	v_cndmask_b32_e64 v113, v113, v181, s[6:7]
	v_mul_f32_e32 v114, 0x3e38aa3b, v114
	s_and_b64 s[8:9], s[74:75], s[8:9]
	v_mul_f32_e32 v115, 0x3e38aa3b, v115
	s_and_b64 s[10:11], s[74:75], s[10:11]
	v_max3_f32 v70, v70, v112, v113
	v_cndmask_b32_e64 v114, v114, v181, s[8:9]
	v_cndmask_b32_e64 v118, v115, v181, s[10:11]
	v_max3_f32 v70, v70, v114, v118
	v_mov_b32_e32 v115, v70
	s_nop 1
	v_permlane16_swap_b32_e32 v70, v115
	v_max_f32_e32 v115, v115, v115
	v_max_f32_e32 v70, v70, v70
	v_max_f32_e32 v70, v70, v115
	v_mov_b32_e32 v115, v70
	s_nop 1
	v_permlane32_swap_b32_e32 v70, v115
	v_max3_f32 v140, v73, v70, v115
	v_sub_f32_e32 v68, v68, v140
	v_exp_f32_e32 v139, v68
	v_sub_f32_e32 v68, v69, v140
	v_exp_f32_e32 v137, v68
	v_sub_f32_e32 v68, v71, v140
	v_exp_f32_e32 v135, v68
	v_sub_f32_e32 v68, v72, v140
	v_exp_f32_e32 v133, v68
	v_sub_f32_e32 v68, v74, v140
	v_exp_f32_e32 v131, v68
	v_sub_f32_e32 v68, v75, v140
	v_exp_f32_e32 v129, v68
	v_sub_f32_e32 v68, v106, v140
	v_exp_f32_e32 v127, v68
	v_sub_f32_e32 v68, v116, v140
	v_exp_f32_e32 v125, v68
	v_sub_f32_e32 v68, v108, v140
	v_add_u32_e32 v108, 0x83, v166
	v_cmp_gt_u32_e64 s[40:41], s39, v108
	v_mul_f32_e32 v76, 0x3e38aa3b, v76
	s_and_b64 s[40:41], s[74:75], s[40:41]
	v_add_u32_e32 v108, 0x82, v166
	v_exp_f32_e32 v123, v68
	v_sub_f32_e32 v68, v109, v140
	v_cndmask_b32_e64 v76, v76, v181, s[40:41]
	v_cmp_gt_u32_e64 s[40:41], s39, v108
	v_exp_f32_e32 v121, v68
	v_sub_f32_e32 v68, v110, v140
	v_mul_f32_e32 v77, 0x3e38aa3b, v77
	s_and_b64 s[40:41], s[74:75], s[40:41]
	v_add_u32_e32 v110, 0x81, v166
	v_cndmask_b32_e64 v77, v77, v181, s[40:41]
	v_cmp_gt_u32_e64 s[40:41], s39, v110
	v_mul_f32_e32 v78, 0x3e38aa3b, v78
	s_and_b64 s[40:41], s[74:75], s[40:41]
	v_cndmask_b32_e64 v110, v78, v181, s[40:41]
	v_mul_f32_e32 v78, 0x3e38aa3b, v79
	v_add_u32_e32 v79, 0x80, v166
	v_cmp_gt_u32_e64 s[40:41], s39, v79
	s_and_b64 s[40:41], s[74:75], s[40:41]
	v_max3_f32 v108, v76, s68, v77
	v_cndmask_b32_e64 v79, v78, v181, s[40:41]
	v_mul_f32_e32 v80, 0x3e38aa3b, v80
	v_mul_f32_e32 v81, 0x3e38aa3b, v81
	v_exp_f32_e32 v119, v68
	v_sub_f32_e32 v68, v111, v140
	v_max3_f32 v78, v108, v110, v79
	v_cndmask_b32_e64 v80, v80, v181, s[12:13]
	v_cndmask_b32_e64 v81, v81, v181, s[14:15]
	v_mul_f32_e32 v82, 0x3e38aa3b, v82
	v_mul_f32_e32 v83, 0x3e38aa3b, v83
	v_exp_f32_e32 v115, v68
	v_sub_f32_e32 v68, v112, v140
	v_max3_f32 v78, v78, v80, v81
	v_cndmask_b32_e64 v82, v82, v181, s[16:17]
	v_cndmask_b32_e64 v83, v83, v181, s[18:19]
	v_mul_f32_e32 v84, 0x3e38aa3b, v84
	v_mul_f32_e32 v85, 0x3e38aa3b, v85
	v_exp_f32_e32 v111, v68
	v_sub_f32_e32 v68, v113, v140
	v_max3_f32 v78, v78, v82, v83
	v_cndmask_b32_e64 v84, v84, v181, s[20:21]
	v_cndmask_b32_e64 v85, v85, v181, s[22:23]
	v_mul_f32_e32 v86, 0x3e38aa3b, v86
	v_mul_f32_e32 v87, 0x3e38aa3b, v87
	v_exp_f32_e32 v109, v68
	v_sub_f32_e32 v68, v114, v140
	v_max3_f32 v78, v78, v84, v85
	v_cndmask_b32_e64 v86, v86, v181, s[24:25]
	v_cndmask_b32_e64 v87, v87, v181, s[26:27]
	v_mul_f32_e32 v108, 0x3e38aa3b, v142
	v_mul_f32_e32 v112, 0x3e38aa3b, v143
	v_mul_f32_e32 v114, 0x3e38aa3b, v144
	v_max3_f32 v78, v78, v86, v87
	v_cndmask_b32_e64 v108, v108, v181, s[28:29]
	v_cndmask_b32_e64 v112, v112, v181, s[30:31]
	v_cndmask_b32_e64 v116, v114, v181, s[34:35]
	v_mul_f32_e32 v114, 0x3e38aa3b, v145
	v_max3_f32 v78, v78, v108, v112
	v_cndmask_b32_e64 v141, v114, v181, s[36:37]
	v_max3_f32 v78, v78, v116, v141
	v_mov_b32_e32 v114, v78
	s_nop 1
	v_permlane16_swap_b32_e32 v78, v114
	v_max_f32_e32 v114, v114, v114
	v_max_f32_e32 v78, v78, v78
	v_max_f32_e32 v78, v78, v114
	v_mov_b32_e32 v114, v78
	s_nop 1
	v_permlane32_swap_b32_e32 v78, v114
	v_max3_f32 v78, v167, v78, v114
	v_sub_f32_e32 v76, v76, v78
	v_exp_f32_e32 v138, v76
	v_sub_f32_e32 v76, v77, v78
	v_exp_f32_e32 v136, v76
	v_sub_f32_e32 v76, v110, v78
	v_exp_f32_e32 v134, v76
	v_sub_f32_e32 v76, v79, v78
	v_exp_f32_e32 v132, v76
	v_sub_f32_e32 v76, v80, v78
	v_exp_f32_e32 v130, v76
	v_sub_f32_e32 v76, v81, v78
	v_exp_f32_e32 v128, v76
	v_sub_f32_e32 v76, v82, v78
	v_exp_f32_e32 v126, v76
	v_sub_f32_e32 v76, v83, v78
	v_exp_f32_e32 v124, v76
	v_sub_f32_e32 v76, v84, v78
	v_exp_f32_e32 v122, v76
	v_sub_f32_e32 v76, v85, v78
	v_exp_f32_e32 v120, v76
	v_sub_f32_e32 v76, v86, v78
	v_exp_f32_e32 v117, v68
	v_sub_f32_e32 v68, v118, v140
	v_exp_f32_e32 v118, v76
	v_sub_f32_e32 v76, v87, v78
	v_exp_f32_e32 v114, v76
	v_sub_f32_e32 v76, v108, v78
	v_sub_f32_e32 v77, v116, v78
	v_sub_f32_e32 v70, v73, v140
	v_sub_f32_e32 v142, v167, v78
	v_exp_f32_e32 v110, v76
	v_sub_f32_e32 v76, v112, v78
	v_exp_f32_e32 v116, v77
	v_sub_f32_e32 v77, v141, v78
	v_exp_f32_e32 v106, v70
	v_exp_f32_e32 v113, v68
	v_exp_f32_e32 v108, v76
	v_exp_f32_e32 v76, v142
	v_exp_f32_e32 v112, v77
	v_pk_mul_f32 v[58:59], v[58:59], v[106:107] op_sel_hi:[1,0]
	v_pk_mul_f32 v[56:57], v[56:57], v[106:107] op_sel_hi:[1,0]
	v_pk_mul_f32 v[54:55], v[54:55], v[106:107] op_sel_hi:[1,0]
	v_pk_mul_f32 v[52:53], v[52:53], v[106:107] op_sel_hi:[1,0]
	v_pk_mul_f32 v[62:63], v[62:63], v[106:107] op_sel_hi:[1,0]
	v_pk_mul_f32 v[60:61], v[60:61], v[106:107] op_sel_hi:[1,0]
	v_pk_mul_f32 v[70:71], v[66:67], v[106:107] op_sel_hi:[1,0]
	v_pk_mul_f32 v[68:69], v[64:65], v[106:107] op_sel_hi:[1,0]
	v_cvt_pk_bf16_f32 v72, v139, v137
	v_cvt_pk_bf16_f32 v73, v135, v133
	v_cvt_pk_bf16_f32 v74, v131, v129
	v_cvt_pk_bf16_f32 v75, v127, v125
	v_cvt_pk_bf16_f32 v64, v123, v121
	v_cvt_pk_bf16_f32 v65, v119, v115
	v_cvt_pk_bf16_f32 v66, v111, v109
	v_cvt_pk_bf16_f32 v67, v117, v113
	v_pk_mul_f32 v[42:43], v[42:43], v[76:77] op_sel_hi:[1,0]
	v_pk_mul_f32 v[40:41], v[40:41], v[76:77] op_sel_hi:[1,0]
	v_pk_mul_f32 v[38:39], v[38:39], v[76:77] op_sel_hi:[1,0]
	v_pk_mul_f32 v[36:37], v[36:37], v[76:77] op_sel_hi:[1,0]
	v_pk_mul_f32 v[46:47], v[46:47], v[76:77] op_sel_hi:[1,0]
	v_pk_mul_f32 v[44:45], v[44:45], v[76:77] op_sel_hi:[1,0]
	v_pk_mul_f32 v[50:51], v[50:51], v[76:77] op_sel_hi:[1,0]
	v_pk_mul_f32 v[48:49], v[48:49], v[76:77] op_sel_hi:[1,0]
	v_cvt_pk_bf16_f32 v80, v138, v136
	v_cvt_pk_bf16_f32 v81, v134, v132
	v_cvt_pk_bf16_f32 v82, v130, v128
	v_cvt_pk_bf16_f32 v83, v126, v124
	v_cvt_pk_bf16_f32 v84, v122, v120
	v_cvt_pk_bf16_f32 v85, v118, v114
	v_cvt_pk_bf16_f32 v86, v110, v108
	v_cvt_pk_bf16_f32 v87, v116, v112
	s_setprio 1
	v_add3_u32 v77, s83, v164, v165
	ds_read_b64_tr_b16 v[206:207], v77 offset:20992
	ds_read_b64_tr_b16 v[204:205], v77 offset:18432
	ds_read_b64_tr_b16 v[208:209], v77 offset:18464
	ds_read_b64_tr_b16 v[210:211], v77 offset:21024
	ds_read_b64_tr_b16 v[212:213], v77 offset:23552
	ds_read_b64_tr_b16 v[214:215], v77 offset:26112
	ds_read_b64_tr_b16 v[216:217], v77 offset:23584
	ds_read_b64_tr_b16 v[218:219], v77 offset:26144
	ds_read_b64_tr_b16 v[220:221], v77 offset:18496
	ds_read_b64_tr_b16 v[222:223], v77 offset:21056
	ds_read_b64_tr_b16 v[224:225], v77 offset:23616
	ds_read_b64_tr_b16 v[226:227], v77 offset:26176
	ds_read_b64_tr_b16 v[228:229], v77 offset:18528
	ds_read_b64_tr_b16 v[230:231], v77 offset:21088
	ds_read_b64_tr_b16 v[232:233], v77 offset:23648
	ds_read_b64_tr_b16 v[234:235], v77 offset:26208
	s_waitcnt lgkmcnt(14)
	v_mfma_f32_16x16x32_bf16 v[56:59], v[204:207], v[72:75], v[56:59]
	v_mfma_f32_16x16x32_bf16 v[40:43], v[204:207], v[80:83], v[40:43]
	s_waitcnt lgkmcnt(10)
	v_mfma_f32_16x16x32_bf16 v[56:59], v[212:215], v[64:67], v[56:59]
	v_mfma_f32_16x16x32_bf16 v[40:43], v[212:215], v[84:87], v[40:43]
	v_mfma_f32_16x16x32_bf16 v[52:55], v[208:211], v[72:75], v[52:55]
	v_mfma_f32_16x16x32_bf16 v[36:39], v[208:211], v[80:83], v[36:39]
	s_waitcnt lgkmcnt(8)
	v_mfma_f32_16x16x32_bf16 v[52:55], v[216:219], v[64:67], v[52:55]
	v_mfma_f32_16x16x32_bf16 v[36:39], v[216:219], v[84:87], v[36:39]
	s_waitcnt lgkmcnt(6)
	v_mfma_f32_16x16x32_bf16 v[60:63], v[220:223], v[72:75], v[60:63]
	v_mfma_f32_16x16x32_bf16 v[44:47], v[220:223], v[80:83], v[44:47]
	s_waitcnt lgkmcnt(4)
	v_mfma_f32_16x16x32_bf16 v[60:63], v[224:227], v[64:67], v[60:63]
	v_mfma_f32_16x16x32_bf16 v[44:47], v[224:227], v[84:87], v[44:47]
	s_waitcnt lgkmcnt(2)
	v_mfma_f32_16x16x32_bf16 v[68:71], v[228:231], v[72:75], v[68:71]
	v_mfma_f32_16x16x32_bf16 v[48:51], v[228:231], v[80:83], v[48:51]
	s_waitcnt lgkmcnt(0)
	v_mfma_f32_16x16x32_bf16 v[64:67], v[232:235], v[64:67], v[68:71]
	v_mfma_f32_16x16x32_bf16 v[48:51], v[232:235], v[84:87], v[48:51]
	s_nop 3
	s_setprio 0
	s_setprio 1
	ds_read_b128 v[204:207], v88 offset:9216
	ds_read_b128 v[208:211], v88 offset:9280
	ds_read_b128 v[212:215], v88 offset:11520
	ds_read_b128 v[216:219], v88 offset:13824
	ds_read_b128 v[220:223], v88 offset:16128
	ds_read_b128 v[224:227], v88 offset:11584
	ds_read_b128 v[228:231], v88 offset:13888
	ds_read_b128 v[232:235], v88 offset:16192
	s_waitcnt lgkmcnt(7)
	v_mfma_f32_16x16x32_bf16 v[72:75], v[204:207], v[4:7], v[0:3]
	v_mfma_f32_16x16x32_bf16 v[68:71], v[204:207], v[12:15], v[0:3]
	s_waitcnt lgkmcnt(6)
	v_mfma_f32_16x16x32_bf16 v[168:171], v[208:211], v[16:19], v[68:71]
	v_mfma_f32_16x16x32_bf16 v[72:75], v[208:211], v[8:11], v[72:75]
	s_waitcnt lgkmcnt(5)
	v_mfma_f32_16x16x32_bf16 v[84:87], v[212:215], v[4:7], v[0:3]
	v_mfma_f32_16x16x32_bf16 v[80:83], v[212:215], v[12:15], v[0:3]
	s_waitcnt lgkmcnt(2)
	v_mfma_f32_16x16x32_bf16 v[84:87], v[224:227], v[8:11], v[84:87]
	v_mfma_f32_16x16x32_bf16 v[184:187], v[224:227], v[16:19], v[80:83]
	v_mfma_f32_16x16x32_bf16 v[146:149], v[216:219], v[4:7], v[0:3]
	v_mfma_f32_16x16x32_bf16 v[142:145], v[216:219], v[12:15], v[0:3]
	s_waitcnt lgkmcnt(1)
	v_mfma_f32_16x16x32_bf16 v[80:83], v[228:231], v[8:11], v[146:149]
	v_mfma_f32_16x16x32_bf16 v[188:191], v[228:231], v[16:19], v[142:145]
	v_mfma_f32_16x16x32_bf16 v[154:157], v[220:223], v[4:7], v[0:3]
	v_mfma_f32_16x16x32_bf16 v[150:153], v[220:223], v[12:15], v[0:3]
	s_waitcnt lgkmcnt(0)
	v_mfma_f32_16x16x32_bf16 v[142:145], v[232:235], v[8:11], v[154:157]
	v_mfma_f32_16x16x32_bf16 v[192:195], v[232:235], v[16:19], v[150:153]
	s_nop 0
	s_setprio 0
	v_mul_f32_e32 v68, 0x3e38aa3b, v72
	v_add_u32_e32 v69, 51, v166
	v_mul_f32_e32 v71, 0x3e38aa3b, v74
	v_add_u32_e32 v72, 49, v166
	v_add_u32_e32 v74, 35, v166
	v_cmp_gt_u32_e64 s[12:13], s39, v69
	v_mul_f32_e32 v69, 0x3e38aa3b, v73
	v_cmp_gt_u32_e64 s[16:17], s39, v72
	v_mul_f32_e32 v72, 0x3e38aa3b, v75
	v_add_u32_e32 v73, 48, v166
	v_cmp_gt_u32_e64 s[20:21], s39, v74
	v_add_u32_e32 v75, 34, v166
	v_cmp_gt_u32_e64 s[18:19], s39, v73
	v_mul_f32_e32 v73, 0x3e38aa3b, v84
	s_and_b64 s[20:21], s[74:75], s[20:21]
	v_cmp_gt_u32_e64 s[22:23], s39, v75
	v_add_u32_e32 v79, 33, v166
	v_cndmask_b32_e64 v74, v73, v181, s[20:21]
	v_mul_f32_e32 v73, 0x3e38aa3b, v85
	s_and_b64 s[22:23], s[74:75], s[22:23]
	v_cmp_gt_u32_e64 s[24:25], s39, v79
	v_add_u32_e32 v84, 32, v166
	v_cndmask_b32_e64 v75, v73, v181, s[22:23]
	v_mul_f32_e32 v73, 0x3e38aa3b, v86
	s_and_b64 s[24:25], s[74:75], s[24:25]
	v_cmp_gt_u32_e64 s[26:27], s39, v84
	v_cndmask_b32_e64 v79, v73, v181, s[24:25]
	v_mul_f32_e32 v73, 0x3e38aa3b, v87
	s_and_b64 s[26:27], s[74:75], s[26:27]
	v_cndmask_b32_e64 v84, v73, v181, s[26:27]
	v_mul_f32_e32 v73, 0x3e38aa3b, v80
	v_add_u32_e32 v80, 19, v166
	v_cmp_gt_u32_e64 s[28:29], s39, v80
	s_and_b64 s[28:29], s[74:75], s[28:29]
	v_add_u32_e32 v70, 50, v166
	v_cndmask_b32_e64 v80, v73, v181, s[28:29]
	v_mul_f32_e32 v73, 0x3e38aa3b, v81
	v_add_u32_e32 v81, 18, v166
	v_cmp_gt_u32_e64 s[30:31], s39, v81
	s_and_b64 s[30:31], s[74:75], s[30:31]
	v_cmp_gt_u32_e64 s[14:15], s39, v70
	v_cndmask_b32_e64 v81, v73, v181, s[30:31]
	v_mul_f32_e32 v73, 0x3e38aa3b, v82
	v_add_u32_e32 v82, 17, v166
	v_cmp_gt_u32_e64 s[34:35], s39, v82
	s_and_b64 s[34:35], s[74:75], s[34:35]
	v_add_u32_e32 v85, 3, v166
	v_cndmask_b32_e64 v82, v73, v181, s[34:35]
	v_mul_f32_e32 v73, 0x3e38aa3b, v83
	v_add_u32_e32 v83, 16, v166
	v_cmp_gt_u32_e64 s[36:37], s39, v83
	s_and_b64 s[12:13], s[74:75], s[12:13]
	s_and_b64 s[14:15], s[74:75], s[14:15]
	s_and_b64 s[36:37], s[74:75], s[36:37]
	v_cmp_gt_u32_e64 s[40:41], s39, v85
	v_cndmask_b32_e64 v68, v68, v181, s[12:13]
	v_cndmask_b32_e64 v69, v69, v181, s[14:15]
	s_and_b64 s[16:17], s[74:75], s[16:17]
	s_and_b64 s[18:19], s[74:75], s[18:19]
	v_cndmask_b32_e64 v83, v73, v181, s[36:37]
	v_mul_f32_e32 v73, 0x3e38aa3b, v142
	s_and_b64 s[40:41], s[74:75], s[40:41]
	v_add_u32_e32 v86, 2, v166
	v_max3_f32 v70, v68, s68, v69
	v_cndmask_b32_e64 v71, v71, v181, s[16:17]
	v_cndmask_b32_e64 v72, v72, v181, s[18:19]
	v_cndmask_b32_e64 v85, v73, v181, s[40:41]
	v_cmp_gt_u32_e64 s[40:41], s39, v86
	v_max3_f32 v70, v70, v71, v72
	v_mul_f32_e32 v73, 0x3e38aa3b, v143
	s_and_b64 s[40:41], s[74:75], s[40:41]
	v_add_u32_e32 v87, 1, v166
	v_max3_f32 v70, v70, v74, v75
	v_cndmask_b32_e64 v86, v73, v181, s[40:41]
	v_cmp_gt_u32_e64 s[40:41], s39, v87
	v_max3_f32 v70, v70, v79, v84
	v_mul_f32_e32 v73, 0x3e38aa3b, v144
	s_and_b64 s[40:41], s[74:75], s[40:41]
	v_max3_f32 v70, v70, v80, v81
	v_cndmask_b32_e64 v88, v73, v181, s[40:41]
	v_cmp_gt_u32_e64 s[40:41], s39, v166
	v_max3_f32 v70, v70, v82, v83
	v_mul_f32_e32 v73, 0x3e38aa3b, v145
	s_and_b64 s[40:41], s[74:75], s[40:41]
	v_max3_f32 v70, v70, v85, v86
	v_cndmask_b32_e64 v142, v73, v181, s[40:41]
	v_max3_f32 v70, v70, v88, v142
	v_mov_b32_e32 v73, v70
	s_nop 1
	v_permlane16_swap_b32_e32 v70, v73
	v_max_f32_e32 v73, v73, v73
	v_max_f32_e32 v70, v70, v70
	v_max_f32_e32 v70, v70, v73
	v_mov_b32_e32 v73, v70
	s_nop 1
	v_permlane32_swap_b32_e32 v70, v73
	v_max3_f32 v73, v140, v70, v73
	v_sub_f32_e32 v68, v68, v73
	v_exp_f32_e32 v159, v68
	v_sub_f32_e32 v68, v69, v73
	v_exp_f32_e32 v157, v68
	v_sub_f32_e32 v68, v71, v73
	v_exp_f32_e32 v155, v68
	v_sub_f32_e32 v68, v72, v73
	v_exp_f32_e32 v153, v68
	v_sub_f32_e32 v68, v74, v73
	v_exp_f32_e32 v151, v68
	v_sub_f32_e32 v68, v75, v73
	v_exp_f32_e32 v149, v68
	v_sub_f32_e32 v68, v79, v73
	v_exp_f32_e32 v147, v68
	v_sub_f32_e32 v68, v84, v73
	v_exp_f32_e32 v145, v68
	v_sub_f32_e32 v68, v80, v73
	v_exp_f32_e32 v143, v68
	v_sub_f32_e32 v68, v81, v73
	v_exp_f32_e32 v141, v68
	v_sub_f32_e32 v68, v82, v73
	v_sub_f32_e32 v70, v140, v73
	v_exp_f32_e32 v87, v68
	v_sub_f32_e32 v68, v83, v73
	v_exp_f32_e32 v83, v68
	v_sub_f32_e32 v68, v85, v73
	v_exp_f32_e32 v72, v70
	v_exp_f32_e32 v79, v68
	v_sub_f32_e32 v68, v86, v73
	v_exp_f32_e32 v75, v68
	v_sub_f32_e32 v68, v88, v73
	v_exp_f32_e32 v85, v68
	v_sub_f32_e32 v68, v142, v73
	v_exp_f32_e32 v81, v68
	v_pk_mul_f32 v[68:69], v[64:65], v[72:73] op_sel_hi:[1,0]
	v_mul_f32_e32 v64, 0x3e38aa3b, v168
	v_cndmask_b32_e32 v74, v64, v181, vcc
	v_mul_f32_e32 v64, 0x3e38aa3b, v169
	v_cndmask_b32_e64 v80, v64, v181, s[6:7]
	v_mul_f32_e32 v64, 0x3e38aa3b, v170
	v_cndmask_b32_e64 v82, v64, v181, s[8:9]
	v_mul_f32_e32 v64, 0x3e38aa3b, v171
	v_cndmask_b32_e64 v84, v64, v181, s[10:11]
	v_mul_f32_e32 v64, 0x3e38aa3b, v184
	v_cndmask_b32_e64 v86, v64, v181, s[12:13]
	v_mul_f32_e32 v64, 0x3e38aa3b, v185
	v_cndmask_b32_e64 v88, v64, v181, s[14:15]
	v_mul_f32_e32 v64, 0x3e38aa3b, v186
	v_cndmask_b32_e64 v140, v64, v181, s[16:17]
	v_mul_f32_e32 v64, 0x3e38aa3b, v187
	v_cndmask_b32_e64 v142, v64, v181, s[18:19]
	v_mul_f32_e32 v64, 0x3e38aa3b, v188
	v_cndmask_b32_e64 v160, v64, v181, s[20:21]
	v_mul_f32_e32 v64, 0x3e38aa3b, v189
	v_cndmask_b32_e64 v161, v64, v181, s[22:23]
	v_mul_f32_e32 v64, 0x3e38aa3b, v190
	v_cndmask_b32_e64 v172, v64, v181, s[24:25]
	v_mul_f32_e32 v64, 0x3e38aa3b, v191
	v_cndmask_b32_e64 v173, v64, v181, s[26:27]
	v_mul_f32_e32 v64, 0x3e38aa3b, v192
	v_cndmask_b32_e64 v184, v64, v181, s[28:29]
	v_mul_f32_e32 v64, 0x3e38aa3b, v193
	v_cndmask_b32_e64 v185, v64, v181, s[30:31]
	v_mul_f32_e32 v64, 0x3e38aa3b, v194
	v_cndmask_b32_e64 v186, v64, v181, s[34:35]
	v_mul_f32_e32 v64, 0x3e38aa3b, v195
	v_cndmask_b32_e64 v187, v64, v181, s[36:37]
	v_max3_f32 v64, v74, s68, v80
	v_max3_f32 v64, v64, v82, v84
	v_max3_f32 v64, v64, v86, v88
	v_max3_f32 v64, v64, v140, v142
	v_max3_f32 v64, v64, v160, v161
	v_max3_f32 v64, v64, v172, v173
	v_max3_f32 v144, v64, v184, v185
	v_max3_f32 v144, v144, v186, v187
	v_mov_b32_e32 v146, v144
	s_nop 1
	v_permlane16_swap_b32_e32 v144, v146
	v_max_f32_e32 v146, v146, v146
	v_max_f32_e32 v144, v144, v144
	v_max_f32_e32 v144, v144, v146
	v_mov_b32_e32 v146, v144
	s_nop 1
	v_permlane32_swap_b32_e32 v144, v146
	v_max3_f32 v167, v78, v144, v146
	v_sub_f32_e32 v74, v74, v167
	v_exp_f32_e32 v158, v74
	v_sub_f32_e32 v74, v80, v167
	v_exp_f32_e32 v156, v74
	v_sub_f32_e32 v74, v82, v167
	v_exp_f32_e32 v154, v74
	v_sub_f32_e32 v74, v84, v167
	v_exp_f32_e32 v152, v74
	v_sub_f32_e32 v74, v86, v167
	v_exp_f32_e32 v150, v74
	v_sub_f32_e32 v74, v88, v167
	v_exp_f32_e32 v148, v74
	v_sub_f32_e32 v74, v140, v167
	v_exp_f32_e32 v146, v74
	v_sub_f32_e32 v74, v142, v167
	v_exp_f32_e32 v144, v74
	v_sub_f32_e32 v74, v160, v167
	v_exp_f32_e32 v142, v74
	v_sub_f32_e32 v74, v161, v167
	v_exp_f32_e32 v140, v74
	v_sub_f32_e32 v74, v172, v167
	v_exp_f32_e32 v86, v74
	v_sub_f32_e32 v74, v173, v167
	v_sub_f32_e32 v188, v78, v167
	v_exp_f32_e32 v82, v74
	v_sub_f32_e32 v74, v184, v167
	v_sub_f32_e32 v80, v186, v167
	v_exp_f32_e32 v78, v74
	v_sub_f32_e32 v74, v185, v167
	v_exp_f32_e32 v160, v188
	v_exp_f32_e32 v84, v80
	v_sub_f32_e32 v80, v187, v167
	v_exp_f32_e32 v74, v74
	v_exp_f32_e32 v80, v80
	v_pk_mul_f32 v[58:59], v[58:59], v[72:73] op_sel_hi:[1,0]
	v_pk_mul_f32 v[56:57], v[56:57], v[72:73] op_sel_hi:[1,0]
	v_pk_mul_f32 v[54:55], v[54:55], v[72:73] op_sel_hi:[1,0]
	v_pk_mul_f32 v[52:53], v[52:53], v[72:73] op_sel_hi:[1,0]
	v_pk_mul_f32 v[62:63], v[62:63], v[72:73] op_sel_hi:[1,0]
	v_pk_mul_f32 v[60:61], v[60:61], v[72:73] op_sel_hi:[1,0]
	v_pk_mul_f32 v[70:71], v[66:67], v[72:73] op_sel_hi:[1,0]
	v_cvt_pk_bf16_f32 v64, v143, v141
	v_cvt_pk_bf16_f32 v65, v87, v83
	v_cvt_pk_bf16_f32 v66, v79, v75
	v_cvt_pk_bf16_f32 v67, v85, v81
	v_pk_mul_f32 v[42:43], v[42:43], v[160:161] op_sel_hi:[1,0]
	v_pk_mul_f32 v[40:41], v[40:41], v[160:161] op_sel_hi:[1,0]
	v_pk_mul_f32 v[38:39], v[38:39], v[160:161] op_sel_hi:[1,0]
	v_pk_mul_f32 v[36:37], v[36:37], v[160:161] op_sel_hi:[1,0]
	v_pk_mul_f32 v[46:47], v[46:47], v[160:161] op_sel_hi:[1,0]
	v_pk_mul_f32 v[44:45], v[44:45], v[160:161] op_sel_hi:[1,0]
	v_pk_mul_f32 v[50:51], v[50:51], v[160:161] op_sel_hi:[1,0]
	v_pk_mul_f32 v[48:49], v[48:49], v[160:161] op_sel_hi:[1,0]
	v_cvt_pk_bf16_f32 v168, v159, v157
	v_cvt_pk_bf16_f32 v169, v155, v153
	v_cvt_pk_bf16_f32 v170, v151, v149
	v_cvt_pk_bf16_f32 v171, v147, v145
	v_cvt_pk_bf16_f32 v184, v158, v156
	v_cvt_pk_bf16_f32 v185, v154, v152
	v_cvt_pk_bf16_f32 v186, v150, v148
	v_cvt_pk_bf16_f32 v187, v146, v144
	v_cvt_pk_bf16_f32 v188, v142, v140
	v_cvt_pk_bf16_f32 v189, v86, v82
	v_cvt_pk_bf16_f32 v190, v78, v74
	v_cvt_pk_bf16_f32 v191, v84, v80
	s_setprio 1
	ds_read_b64_tr_b16 v[206:207], v77 offset:31232
	ds_read_b64_tr_b16 v[204:205], v77 offset:28672
	ds_read_b64_tr_b16 v[208:209], v77 offset:28704
	ds_read_b64_tr_b16 v[210:211], v77 offset:31264
	ds_read_b64_tr_b16 v[212:213], v77 offset:33792
	ds_read_b64_tr_b16 v[214:215], v77 offset:36352
	ds_read_b64_tr_b16 v[216:217], v77 offset:33824
	ds_read_b64_tr_b16 v[218:219], v77 offset:36384
	ds_read_b64_tr_b16 v[220:221], v77 offset:28736
	ds_read_b64_tr_b16 v[222:223], v77 offset:31296
	ds_read_b64_tr_b16 v[224:225], v77 offset:33856
	ds_read_b64_tr_b16 v[226:227], v77 offset:36416
	ds_read_b64_tr_b16 v[228:229], v77 offset:28768
	ds_read_b64_tr_b16 v[230:231], v77 offset:31328
	ds_read_b64_tr_b16 v[232:233], v77 offset:33888
	ds_read_b64_tr_b16 v[234:235], v77 offset:36448
	s_waitcnt lgkmcnt(14)
	v_mfma_f32_16x16x32_bf16 v[56:59], v[204:207], v[168:171], v[56:59]
	v_mfma_f32_16x16x32_bf16 v[40:43], v[204:207], v[184:187], v[40:43]
	s_waitcnt lgkmcnt(10)
	v_mfma_f32_16x16x32_bf16 v[56:59], v[212:215], v[64:67], v[56:59]
	v_mfma_f32_16x16x32_bf16 v[40:43], v[212:215], v[188:191], v[40:43]
	v_mfma_f32_16x16x32_bf16 v[52:55], v[208:211], v[168:171], v[52:55]
	v_mfma_f32_16x16x32_bf16 v[36:39], v[208:211], v[184:187], v[36:39]
	s_waitcnt lgkmcnt(8)
	v_mfma_f32_16x16x32_bf16 v[52:55], v[216:219], v[64:67], v[52:55]
	v_mfma_f32_16x16x32_bf16 v[36:39], v[216:219], v[188:191], v[36:39]
	s_waitcnt lgkmcnt(6)
	v_mfma_f32_16x16x32_bf16 v[60:63], v[220:223], v[168:171], v[60:63]
	v_mfma_f32_16x16x32_bf16 v[44:47], v[220:223], v[184:187], v[44:47]
	s_waitcnt lgkmcnt(4)
	v_mfma_f32_16x16x32_bf16 v[60:63], v[224:227], v[64:67], v[60:63]
	v_mfma_f32_16x16x32_bf16 v[44:47], v[224:227], v[188:191], v[44:47]
	s_waitcnt lgkmcnt(2)
	v_mfma_f32_16x16x32_bf16 v[68:71], v[228:231], v[168:171], v[68:71]
	v_mfma_f32_16x16x32_bf16 v[48:51], v[228:231], v[184:187], v[48:51]
	s_waitcnt lgkmcnt(0)
	v_mfma_f32_16x16x32_bf16 v[64:67], v[232:235], v[64:67], v[68:71]
	v_mfma_f32_16x16x32_bf16 v[48:51], v[232:235], v[188:191], v[48:51]
	s_nop 3
	s_setprio 0
	s_add_i32 s12, s82, 1
	s_cmp_ge_i32 s12, s44
	s_cbranch_scc1 .LBB0_3060
	s_bitcmp1_b32 s12, 0
	s_cselect_b32 s6, 0x9800, 0
	v_add3_u32 v71, s6, v99, v98
	v_add3_u32 v68, s6, v162, v98
	v_add3_u32 v69, s6, v107, v98
	v_add3_u32 v70, s6, v105, v98
	s_waitcnt vmcnt(0)
	ds_write_b128 v71, v[20:23]
	ds_write_b128 v70, v[24:27]
	ds_write_b128 v69, v[28:31] offset:18432
	ds_write_b128 v68, v[32:35] offset:18432

.LBB0_3076:
	s_or_b64 exec, exec, s[6:7]
	s_add_i32 s8, s10, 0xffffff00
	s_ashr_i32 s9, s8, 31
	s_lshl_b64 s[6:7], s[8:9], 9
	v_readlane_b32 s20, v252, 19
	v_readlane_b32 s21, v252, 20
	s_add_u32 s14, s20, s6
	s_addc_u32 s15, s21, s7
	s_add_u32 s16, s14, 0x20000
	s_addc_u32 s17, s15, 0
	s_mul_hi_i32 s7, s8, 0x3000
	s_mul_i32 s6, s8, 0x3000
	s_lshl_b64 s[12:13], s[6:7], 1
	v_readlane_b32 s20, v252, 17
	v_readlane_b32 s21, v252, 18
	s_add_u32 s12, s20, s12
	s_addc_u32 s13, s21, s13
	s_movk_i32 s11, 0xff
	s_movk_i32 s20, 0x100
	v_sub_u32_e32 v10, 0x11f, v8
	v_add_u32_e32 v11, -1, v10
	v_med3_i32 v20, v10, 0, s11
	v_med3_i32 v21, v11, 0, s11
	v_lshlrev_b32_e32 v20, 1, v20
	v_lshlrev_b32_e32 v21, 1, v21
	global_load_ushort v30, v20, s[14:15]
	global_load_ushort v31, v21, s[14:15]
	global_load_ushort v32, v20, s[16:17]
	global_load_ushort v33, v21, s[16:17]
	v_lshlrev_b32_e32 v6, 4, v8
	global_load_dwordx4 v[70:73], v6, s[12:13]
	v_lshrrev_b32_e32 v4, 5, v8
	v_lshl_add_u32 v50, v8, 4, v183
	v_lshl_add_u32 v50, v4, 10, v50
	v_lshlrev_b32_e32 v51, 1, v8
	s_waitcnt vmcnt(1)
	v_cmp_gt_u32_e32 vcc, 0x100, v10
	v_cmp_gt_u32_e64 s[18:19], s20, v11
	s_nop 1
	v_cndmask_b32_e32 v30, 0, v30, vcc
	v_cndmask_b32_e32 v32, 0, v32, vcc
	v_cndmask_b32_e64 v31, 0, v31, s[18:19]
	v_cndmask_b32_e64 v33, 0, v33, s[18:19]
	v_cmp_gt_u32_e32 vcc, 0x130, v8
	s_and_saveexec_b64 s[18:19], vcc
	ds_write_b16 v51, v30
	ds_write_b16 v51, v31 offset:608
	ds_write_b16 v51, v32 offset:1216
	ds_write_b16 v51, v33 offset:1824
	s_or_b64 exec, exec, s[18:19]
	s_waitcnt lgkmcnt(0)
	s_barrier
	s_waitcnt vmcnt(0)
	ds_write_b128 v50, v[70:73]
	s_mov_b64 s[8:9], exec
